# queue-order-pool-near-tail+pool-unit-v2-double-buffered-dma
# speedup vs baseline: 1.0794x; 1.0141x over previous
.LBB0_36:
	s_or_b64 exec, exec, s[10:11]
	s_mov_b64 s[10:11], src_shared_base
	s_xor_b64 s[40:41], s[66:67], -1
	s_xor_b64 s[44:45], s[20:21], -1
	s_add_i32 s10, 0, 0x20200
	s_cmp_lg_u32 s10, -1
	s_cselect_b32 s10, s10, 0
	s_cselect_b32 s11, s11, 0
	v_mov_b32_e32 v2, s10
	s_waitcnt lgkmcnt(0)
	v_mov_b32_e32 v3, s11
	s_waitcnt lgkmcnt(0)
	s_barrier
	flat_load_dword v0, v[2:3] sc0 sc1
	s_waitcnt vmcnt(0)
	s_mov_b64 s[38:39], -1
	s_waitcnt lgkmcnt(0)
	v_cmp_gt_i32_e32 vcc, s69, v0
	s_and_saveexec_b64 s[10:11], vcc
	s_cbranch_execz .LBB0_31
	s_cmpk_eq_i32 s69, 0x340
	s_cselect_b32 s18, 0x48, 0
	v_cmp_lt_u32_e32 vcc, 0xff, v0
	v_mov_b32_e32 v2, s18
	s_nop 0
	v_cndmask_b32_e32 v2, 0, v2, vcc
	v_add_u32_e32 v0, v0, v2
	v_mov_b32_e32 v2, 0xffffff78
	v_mov_b32_e32 v3, 0xfffffff8
	v_cmp_gt_u32_e32 vcc, 0x348, v0
	s_nop 1
	v_cndmask_b32_e32 v2, v2, v3, vcc
	v_mov_b32_e32 v3, 0xffffffb8
	v_cmp_gt_u32_e32 vcc, 0x308, v0
	s_nop 1
	v_cndmask_b32_e32 v2, v2, v3, vcc
	v_mov_b32_e32 v3, 0xffffffb8
	v_cmp_gt_u32_e32 vcc, 0x2a8, v0
	s_nop 1
	v_cndmask_b32_e32 v2, v2, v3, vcc
	v_mov_b32_e32 v3, 0xffffffb8
	v_cmp_gt_u32_e32 vcc, 0x1a8, v0
	s_nop 1
	v_cndmask_b32_e32 v2, v2, v3, vcc
	v_mov_b32_e32 v3, 0x240
	v_cmp_gt_u32_e32 vcc, 0x148, v0
	s_nop 1
	v_cndmask_b32_e32 v2, v2, v3, vcc
	v_mov_b32_e32 v3, 0x0
	v_cmp_gt_u32_e32 vcc, 0x100, v0
	s_nop 1
	v_cndmask_b32_e32 v2, v2, v3, vcc
	v_add_u32_e32 v0, v0, v2
	s_movk_i32 s18, 0x340
	v_cmp_gt_i32_e32 vcc, s18, v0
	s_and_saveexec_b64 s[38:39], vcc
	s_xor_b64 s[38:39], exec, s[38:39]
	v_writelane_b32 v250, s38, 35
	s_nop 1
	v_writelane_b32 v250, s39, 36
	s_cbranch_execz .LBB0_259
	s_movk_i32 s18, 0x260
	v_add_u32_e32 v2, 0xfffffea0, v0
	v_cmp_gt_i32_e32 vcc, s18, v0
	s_movk_i32 s18, 0x1a0
	s_mov_b64 s[42:43], 0
	v_cndmask_b32_e32 v3, v218, v219, vcc
	v_cmp_gt_u32_e32 vcc, s18, v2
	s_movk_i32 s18, 0x1ff
	s_nop 0
	v_cndmask_b32_e32 v2, 0, v3, vcc
	v_add_u32_e32 v2, v2, v0
	v_cmp_lt_i32_e64 s[38:39], s18, v2
	s_and_saveexec_b64 s[18:19], s[38:39]
	s_xor_b64 s[18:19], exec, s[18:19]
	s_cbranch_execz .LBB0_57
	s_and_saveexec_b64 s[24:25], s[44:45]
	s_cbranch_execz .LBB0_56
	s_and_saveexec_b64 s[42:43], s[36:37]
	s_cbranch_execz .LBB0_55
	v_readlane_b32 s44, v252, 2
	v_readlane_b32 s45, v252, 3
	s_load_dword s34, s[44:45], 0x10
	s_load_dword s46, s[44:45], 0x0
	s_waitcnt lgkmcnt(0)
	s_lshr_b32 s34, s34, 16
	s_cmp_lg_u32 s34, 0
	s_cselect_b64 s[44:45], -1, 0
	s_cmp_lg_u64 s[44:45], 0
	s_addc_u32 s34, s46, 0
	s_mov_b32 s46, 0x1000000
	s_branch .LBB0_44

.LBB0_80:
	s_movk_i32 s34, 0x2ff
	v_writelane_b32 v250, s40, 37
	v_cmp_lt_u32_e32 vcc, s34, v2
	s_nop 0
	v_writelane_b32 v250, s41, 38
	s_and_saveexec_b64 s[38:39], vcc
	s_xor_b64 s[38:39], exec, s[38:39]
	s_cbranch_execz .LBB0_170
	v_writelane_b32 v250, s38, 39
	v_and_b32_e32 v0, 63, v128
	v_writelane_b32 v250, s39, 40
	v_readfirstlane_b32 s40, v2
	v_readfirstlane_b32 s41, v128
	s_mov_b32 s59, m0
	s_sub_i32 s40, s40, 0x300
	s_lshl_b32 s40, s40, 8
	s_lshr_b32 s41, s41, 6
	s_and_b32 s42, s40, 0xfff
	s_or_b32 s42, s42, s41
	s_cmp_eq_u32 s42, 0
	s_cselect_b32 s42, 1, 0
	v_lshrrev_b32_e32 v2, 3, v0
	v_and_b32_e32 v3, 7, v0
	v_lshlrev_b32_e32 v4, 9, v2
	v_lshl_or_b32 v6, v3, 4, v4
	v_mov_b32_e32 v7, 0
	s_lshl_b32 s43, s41, 2
	v_lshrrev_b32_e32 v4, 4, v0
	v_add_u32_e32 v4, s43, v4
	v_and_b32_e32 v4, 7, v4
	v_xor_b32_e32 v4, v4, v3
	v_lshlrev_b32_e32 v4, 4, v4
	v_lshl_add_u32 v45, v2, 7, v4
	s_lshl_b32 s43, s41, 10
	v_add_u32_e32 v45, s43, v45
	s_lshl_b32 s43, s41, 12
	v_lshl_add_u32 v8, v0, 1, s43
	s_mul_i32 s43, s41, 0x1200
	s_add_i32 s43, s43, 0x11000
	v_lshl_add_u32 v9, v0, 1, s43
	v_and_b32_e32 v2, 31, v0
	v_lshrrev_b32_e32 v3, 5, v0
	v_mul_u32_u24_e32 v44, 0x90, v2
	v_lshl_add_u32 v44, v3, 4, v44
	v_add_u32_e32 v44, s43, v44
	s_lshl_b32 s43, s41, 16
	v_lshlrev_b32_e32 v10, 11, v2
	v_lshl_add_u32 v10, v3, 3, v10
	s_addk_i32 s43, 0x400
	v_add_u32_e32 v10, s43, v10
	v_mov_b32_e32 v11, 0
	s_lshl_b32 s43, s40, 11
	s_add_u32 s52, s70, 0x95c8000
	s_addc_u32 s53, s71, 0
	s_add_u32 s52, s52, s43
	s_addc_u32 s53, s53, 0
	s_sub_i32 s43, s40, 15
	s_lshl_b32 s43, s43, 9
	s_ashr_i32 s49, s43, 31
	s_add_u32 s44, s70, 0x7548000
	s_addc_u32 s45, s71, 0
	s_add_u32 s44, s44, s43
	s_addc_u32 s45, s45, s49
	s_lshl_b32 s43, s41, 12
	s_add_u32 s44, s44, s43
	s_addc_u32 s45, s45, 0
	s_lshl_b32 s48, s41, 10
	s_barrier
	s_add_u32 s46, s44, 0x0
	s_addc_u32 s47, s45, 0
	s_add_i32 s43, s48, 0x0
	v_lshl_add_u64 v[4:5], s[46:47], 0, v[6:7]
	s_mov_b32 m0, s43
	s_nop 0
	global_load_lds_dwordx4 v[4:5], off
	s_add_u32 s46, s44, 0x8000
	s_addc_u32 s47, s45, 0
	s_add_i32 s43, s48, 0x2000
	v_lshl_add_u64 v[4:5], s[46:47], 0, v[6:7]
	s_mov_b32 m0, s43
	s_nop 0
	global_load_lds_dwordx4 v[4:5], off
	s_add_u32 s46, s44, 0x10000
	s_addc_u32 s47, s45, 0
	s_add_i32 s43, s48, 0x4000
	v_lshl_add_u64 v[4:5], s[46:47], 0, v[6:7]
	s_mov_b32 m0, s43
	s_nop 0
	global_load_lds_dwordx4 v[4:5], off
	s_add_u32 s46, s44, 0x18000
	s_addc_u32 s47, s45, 0
	s_add_i32 s43, s48, 0x6000
	v_lshl_add_u64 v[4:5], s[46:47], 0, v[6:7]
	s_mov_b32 m0, s43
	s_nop 0
	global_load_lds_dwordx4 v[4:5], off
	s_cmp_lt_u32 s41, 2
	s_cbranch_scc0 .Lpool_xdma_done0
	s_add_u32 s46, s44, 0x20000
	s_addc_u32 s47, s45, 0
	s_add_i32 s43, s48, 0x8000
	v_lshl_add_u64 v[4:5], s[46:47], 0, v[6:7]
	s_mov_b32 m0, s43
	s_nop 0
	global_load_lds_dwordx4 v[4:5], off
.Lpool_xdma_done0:
	v_readlane_b32 s54, v250, 23
	v_readlane_b32 s55, v250, 24
	v_mov_b32_e32 v2, v45
	v_mov_b32_e32 v3, 0
	s_add_i32 s43, s48, 0x1a000
	v_lshl_add_u64 v[4:5], s[54:55], 0, v[2:3]
	s_mov_b32 m0, s43
	s_nop 0
	global_load_lds_dwordx4 v[4:5], off
	v_lshl_add_u64 v[4:5], s[52:53], 0, v[10:11]
	global_load_dwordx2 v[12:13], v[4:5], off offset:0
	global_load_dwordx2 v[14:15], v[4:5], off offset:16
	global_load_dwordx2 v[16:17], v[4:5], off offset:32
	global_load_dwordx2 v[18:19], v[4:5], off offset:48
	global_load_dwordx2 v[20:21], v[4:5], off offset:64
	global_load_dwordx2 v[22:23], v[4:5], off offset:80
	global_load_dwordx2 v[24:25], v[4:5], off offset:96
	global_load_dwordx2 v[26:27], v[4:5], off offset:112
	s_waitcnt vmcnt(8)
	s_barrier
	s_add_u32 s46, s44, 0x80
	s_addc_u32 s47, s45, 0
	s_add_i32 s43, s48, 0x8800
	v_lshl_add_u64 v[4:5], s[46:47], 0, v[6:7]
	s_mov_b32 m0, s43
	s_nop 0
	global_load_lds_dwordx4 v[4:5], off
	s_add_u32 s46, s44, 0x8080
	s_addc_u32 s47, s45, 0
	s_add_i32 s43, s48, 0xa800
	v_lshl_add_u64 v[4:5], s[46:47], 0, v[6:7]
	s_mov_b32 m0, s43
	s_nop 0
	global_load_lds_dwordx4 v[4:5], off
	s_add_u32 s46, s44, 0x10080
	s_addc_u32 s47, s45, 0
	s_add_i32 s43, s48, 0xc800
	v_lshl_add_u64 v[4:5], s[46:47], 0, v[6:7]
	s_mov_b32 m0, s43
	s_nop 0
	global_load_lds_dwordx4 v[4:5], off
	s_add_u32 s46, s44, 0x18080
	s_addc_u32 s47, s45, 0
	s_add_i32 s43, s48, 0xe800
	v_lshl_add_u64 v[4:5], s[46:47], 0, v[6:7]
	s_mov_b32 m0, s43
	s_nop 0
	global_load_lds_dwordx4 v[4:5], off
	s_cmp_lt_u32 s41, 2
	s_cbranch_scc0 .Lpool_xdma_done1
	s_add_u32 s46, s44, 0x20080
	s_addc_u32 s47, s45, 0
	s_add_i32 s43, s48, 0x10800
	v_lshl_add_u64 v[4:5], s[46:47], 0, v[6:7]
	s_mov_b32 m0, s43
	s_nop 0
	global_load_lds_dwordx4 v[4:5], off
.Lpool_xdma_done1:
	v_readlane_b32 s54, v250, 25
	v_readlane_b32 s55, v250, 26
	v_mov_b32_e32 v2, v45
	v_mov_b32_e32 v3, 0
	s_add_i32 s43, s48, 0x1c000
	v_lshl_add_u64 v[4:5], s[54:55], 0, v[2:3]
	s_mov_b32 m0, s43
	s_nop 0
	global_load_lds_dwordx4 v[4:5], off
	ds_read_u16 v60, v8 offset:1792
	ds_read_u16 v61, v8 offset:1920
	ds_read_u16 v62, v8 offset:2048
	ds_read_u16 v63, v8 offset:2176
	ds_read_u16 v64, v8 offset:2304
	ds_read_u16 v65, v8 offset:2432
	ds_read_u16 v66, v8 offset:2560
	ds_read_u16 v67, v8 offset:2688
	ds_read_u16 v68, v8 offset:2816
	ds_read_u16 v69, v8 offset:2944
	ds_read_u16 v70, v8 offset:3072
	ds_read_u16 v71, v8 offset:3200
	ds_read_u16 v72, v8 offset:3328
	ds_read_u16 v73, v8 offset:3456
	ds_read_u16 v74, v8 offset:3584
	ds_read_u16 v75, v8 offset:3712
	ds_read_u16 v76, v8 offset:3840
	ds_read_u16 v77, v8 offset:3968
	ds_read_u16 v78, v8 offset:4096
	ds_read_u16 v79, v8 offset:4224
	ds_read_u16 v80, v8 offset:4352
	ds_read_u16 v81, v8 offset:4480
	ds_read_u16 v82, v8 offset:4608
	ds_read_u16 v83, v8 offset:4736
	ds_read_u16 v84, v8 offset:4864
	ds_read_u16 v85, v8 offset:4992
	ds_read_u16 v86, v8 offset:5120
	ds_read_u16 v87, v8 offset:5248
	ds_read_u16 v88, v8 offset:5376
	ds_read_u16 v89, v8 offset:5504
	ds_read_u16 v90, v8 offset:5632
	ds_read_u16 v91, v8 offset:5760
	ds_read_u16 v92, v8 offset:5888
	s_mov_b32 s50, 0x3f000000
	s_waitcnt lgkmcnt(0)
	v_lshlrev_b32_e32 v60, 16, v60
	v_lshlrev_b32_e32 v61, 16, v61
	v_lshlrev_b32_e32 v62, 16, v62
	v_lshlrev_b32_e32 v63, 16, v63
	v_lshlrev_b32_e32 v64, 16, v64
	v_lshlrev_b32_e32 v65, 16, v65
	v_lshlrev_b32_e32 v66, 16, v66
	v_lshlrev_b32_e32 v67, 16, v67
	v_lshlrev_b32_e32 v68, 16, v68
	v_lshlrev_b32_e32 v69, 16, v69
	v_lshlrev_b32_e32 v70, 16, v70
	v_lshlrev_b32_e32 v71, 16, v71
	v_lshlrev_b32_e32 v72, 16, v72
	v_lshlrev_b32_e32 v73, 16, v73
	v_lshlrev_b32_e32 v74, 16, v74
	v_lshlrev_b32_e32 v75, 16, v75
	v_lshlrev_b32_e32 v76, 16, v76
	v_lshlrev_b32_e32 v77, 16, v77
	v_lshlrev_b32_e32 v78, 16, v78
	v_lshlrev_b32_e32 v79, 16, v79
	v_lshlrev_b32_e32 v80, 16, v80
	v_lshlrev_b32_e32 v81, 16, v81
	v_lshlrev_b32_e32 v82, 16, v82
	v_lshlrev_b32_e32 v83, 16, v83
	v_lshlrev_b32_e32 v84, 16, v84
	v_lshlrev_b32_e32 v85, 16, v85
	v_lshlrev_b32_e32 v86, 16, v86
	v_lshlrev_b32_e32 v87, 16, v87
	v_lshlrev_b32_e32 v88, 16, v88
	v_lshlrev_b32_e32 v89, 16, v89
	v_lshlrev_b32_e32 v90, 16, v90
	v_lshlrev_b32_e32 v91, 16, v91
	v_lshlrev_b32_e32 v92, 16, v92
	s_cmp_eq_u32 s42, 1
	s_cbranch_scc0 .Lpool_nz0
	v_mov_b32_e32 v60, 0
.Lpool_nz0:
	v_add_f32_e32 v93, v61, v60
	s_cmp_eq_u32 s42, 1
	s_cselect_b32 s51, 0x3f800000, s50
	v_fma_f32 v2, v93, s51, -v61
	v_add_f32_e32 v93, v93, v62
	v_sub_f32_e32 v93, v93, v60
	v_fma_f32 v3, v93, s50, -v62
	v_cvt_pk_bf16_f32 v2, v2, v3
	ds_write_b16 v9, v2 offset:0
	ds_write_b16_d16_hi v9, v2 offset:144
	v_add_f32_e32 v93, v93, v63
	v_sub_f32_e32 v93, v93, v61
	v_fma_f32 v4, v93, s50, -v63
	v_add_f32_e32 v93, v93, v64
	v_sub_f32_e32 v93, v93, v62
	v_fma_f32 v5, v93, s50, -v64
	v_cvt_pk_bf16_f32 v4, v4, v5
	ds_write_b16 v9, v4 offset:288
	ds_write_b16_d16_hi v9, v4 offset:432
	v_add_f32_e32 v93, v93, v65
	v_sub_f32_e32 v93, v93, v63
	v_fma_f32 v2, v93, s50, -v65
	v_add_f32_e32 v93, v93, v66
	v_sub_f32_e32 v93, v93, v64
	v_fma_f32 v3, v93, s50, -v66
	v_cvt_pk_bf16_f32 v2, v2, v3
	ds_write_b16 v9, v2 offset:576
	ds_write_b16_d16_hi v9, v2 offset:720
	v_add_f32_e32 v93, v93, v67
	v_sub_f32_e32 v93, v93, v65
	v_fma_f32 v4, v93, s50, -v67
	v_add_f32_e32 v93, v93, v68
	v_sub_f32_e32 v93, v93, v66
	v_fma_f32 v5, v93, s50, -v68
	v_cvt_pk_bf16_f32 v4, v4, v5
	ds_write_b16 v9, v4 offset:864
	ds_write_b16_d16_hi v9, v4 offset:1008
	v_add_f32_e32 v93, v93, v69
	v_sub_f32_e32 v93, v93, v67
	v_fma_f32 v2, v93, s50, -v69
	v_add_f32_e32 v93, v93, v70
	v_sub_f32_e32 v93, v93, v68
	v_fma_f32 v3, v93, s50, -v70
	v_cvt_pk_bf16_f32 v2, v2, v3
	ds_write_b16 v9, v2 offset:1152
	ds_write_b16_d16_hi v9, v2 offset:1296
	v_add_f32_e32 v93, v93, v71
	v_sub_f32_e32 v93, v93, v69
	v_fma_f32 v4, v93, s50, -v71
	v_add_f32_e32 v93, v93, v72
	v_sub_f32_e32 v93, v93, v70
	v_fma_f32 v5, v93, s50, -v72
	v_cvt_pk_bf16_f32 v4, v4, v5
	ds_write_b16 v9, v4 offset:1440
	ds_write_b16_d16_hi v9, v4 offset:1584
	v_add_f32_e32 v93, v93, v73
	v_sub_f32_e32 v93, v93, v71
	v_fma_f32 v2, v93, s50, -v73
	v_add_f32_e32 v93, v93, v74
	v_sub_f32_e32 v93, v93, v72
	v_fma_f32 v3, v93, s50, -v74
	v_cvt_pk_bf16_f32 v2, v2, v3
	ds_write_b16 v9, v2 offset:1728
	ds_write_b16_d16_hi v9, v2 offset:1872
	v_add_f32_e32 v93, v93, v75
	v_sub_f32_e32 v93, v93, v73
	v_fma_f32 v4, v93, s50, -v75
	v_add_f32_e32 v93, v93, v76
	v_sub_f32_e32 v93, v93, v74
	v_fma_f32 v5, v93, s50, -v76
	v_cvt_pk_bf16_f32 v4, v4, v5
	ds_write_b16 v9, v4 offset:2016
	ds_write_b16_d16_hi v9, v4 offset:2160
	v_add_f32_e32 v93, v93, v77
	v_sub_f32_e32 v93, v93, v75
	v_fma_f32 v2, v93, s50, -v77
	v_add_f32_e32 v93, v93, v78
	v_sub_f32_e32 v93, v93, v76
	v_fma_f32 v3, v93, s50, -v78
	v_cvt_pk_bf16_f32 v2, v2, v3
	ds_write_b16 v9, v2 offset:2304
	ds_write_b16_d16_hi v9, v2 offset:2448
	v_add_f32_e32 v93, v93, v79
	v_sub_f32_e32 v93, v93, v77
	v_fma_f32 v4, v93, s50, -v79
	v_add_f32_e32 v93, v93, v80
	v_sub_f32_e32 v93, v93, v78
	v_fma_f32 v5, v93, s50, -v80
	v_cvt_pk_bf16_f32 v4, v4, v5
	ds_write_b16 v9, v4 offset:2592
	ds_write_b16_d16_hi v9, v4 offset:2736
	v_add_f32_e32 v93, v93, v81
	v_sub_f32_e32 v93, v93, v79
	v_fma_f32 v2, v93, s50, -v81
	v_add_f32_e32 v93, v93, v82
	v_sub_f32_e32 v93, v93, v80
	v_fma_f32 v3, v93, s50, -v82
	v_cvt_pk_bf16_f32 v2, v2, v3
	ds_write_b16 v9, v2 offset:2880
	ds_write_b16_d16_hi v9, v2 offset:3024
	v_add_f32_e32 v93, v93, v83
	v_sub_f32_e32 v93, v93, v81
	v_fma_f32 v4, v93, s50, -v83
	v_add_f32_e32 v93, v93, v84
	v_sub_f32_e32 v93, v93, v82
	v_fma_f32 v5, v93, s50, -v84
	v_cvt_pk_bf16_f32 v4, v4, v5
	ds_write_b16 v9, v4 offset:3168
	ds_write_b16_d16_hi v9, v4 offset:3312
	v_add_f32_e32 v93, v93, v85
	v_sub_f32_e32 v93, v93, v83
	v_fma_f32 v2, v93, s50, -v85
	v_add_f32_e32 v93, v93, v86
	v_sub_f32_e32 v93, v93, v84
	v_fma_f32 v3, v93, s50, -v86
	v_cvt_pk_bf16_f32 v2, v2, v3
	ds_write_b16 v9, v2 offset:3456
	ds_write_b16_d16_hi v9, v2 offset:3600
	v_add_f32_e32 v93, v93, v87
	v_sub_f32_e32 v93, v93, v85
	v_fma_f32 v4, v93, s50, -v87
	v_add_f32_e32 v93, v93, v88
	v_sub_f32_e32 v93, v93, v86
	v_fma_f32 v5, v93, s50, -v88
	v_cvt_pk_bf16_f32 v4, v4, v5
	ds_write_b16 v9, v4 offset:3744
	ds_write_b16_d16_hi v9, v4 offset:3888
	v_add_f32_e32 v93, v93, v89
	v_sub_f32_e32 v93, v93, v87
	v_fma_f32 v2, v93, s50, -v89
	v_add_f32_e32 v93, v93, v90
	v_sub_f32_e32 v93, v93, v88
	v_fma_f32 v3, v93, s50, -v90
	v_cvt_pk_bf16_f32 v2, v2, v3
	ds_write_b16 v9, v2 offset:4032
	ds_write_b16_d16_hi v9, v2 offset:4176
	v_add_f32_e32 v93, v93, v91
	v_sub_f32_e32 v93, v93, v89
	v_fma_f32 v4, v93, s50, -v91
	v_add_f32_e32 v93, v93, v92
	v_sub_f32_e32 v93, v93, v90
	v_fma_f32 v5, v93, s50, -v92
	v_cvt_pk_bf16_f32 v4, v4, v5
	ds_write_b16 v9, v4 offset:4320
	ds_write_b16_d16_hi v9, v4 offset:4464
	v_and_b32_e32 v2, 31, v0
	v_lshrrev_b32_e32 v3, 5, v0
	v_bfe_u32 v4, v0, 1, 3
	v_xor_b32_e32 v3, v3, v4
	v_lshlrev_b32_e32 v2, 7, v2
	v_add_u32_e32 v2, 0x1a000, v2
	v_lshl_add_u32 v5, v3, 4, v2
	v_xor_b32_e32 v4, 2, v3
	v_lshl_add_u32 v4, v4, 4, v2
	v_xor_b32_e32 v88, 4, v3
	v_xor_b32_e32 v3, 6, v3
	v_lshl_add_u32 v3, v3, 4, v2
	v_lshl_add_u32 v2, v88, 4, v2
	s_waitcnt lgkmcnt(0)
	ds_read_b128 v[28:31], v5 offset:0
	ds_read_b128 v[32:35], v5 offset:4096
	ds_read_b128 v[78:81], v44 offset:0
	ds_read_b128 v[82:85], v44 offset:32
	ds_read_b128 v[86:89], v44 offset:64
	ds_read_b128 v[90:93], v44 offset:96
	ds_read_b128 v[36:39], v4 offset:0
	ds_read_b128 v[40:43], v4 offset:4096
	s_waitcnt lgkmcnt(0)
	v_mfma_f32_32x32x16_bf16 v[46:61], v[28:31], v[78:81], 0
	v_mfma_f32_32x32x16_bf16 v[62:77], v[32:35], v[78:81], 0
	ds_read_b128 v[28:31], v2 offset:0
	ds_read_b128 v[32:35], v2 offset:4096
	v_mfma_f32_32x32x16_bf16 v[46:61], v[36:39], v[82:85], v[46:61]
	v_mfma_f32_32x32x16_bf16 v[62:77], v[40:43], v[82:85], v[62:77]
	ds_read_b128 v[36:39], v3 offset:0
	ds_read_b128 v[40:43], v3 offset:4096
	s_waitcnt lgkmcnt(2)
	v_mfma_f32_32x32x16_bf16 v[46:61], v[28:31], v[86:89], v[46:61]
	v_mfma_f32_32x32x16_bf16 v[62:77], v[32:35], v[86:89], v[62:77]
	s_waitcnt lgkmcnt(0)
	v_mfma_f32_32x32x16_bf16 v[46:61], v[36:39], v[90:93], v[46:61]
	v_mfma_f32_32x32x16_bf16 v[62:77], v[40:43], v[90:93], v[62:77]
	v_lshl_add_u64 v[4:5], s[52:53], 0, v[10:11]
	s_nop 14
	s_waitcnt vmcnt(5)
	s_mov_b32 s56, 0xbfb8aa3b
	s_mov_b32 s57, 0xbfb8aa3b
	s_mov_b32 s54, 1.0
	s_mov_b32 s55, 1.0
	v_lshlrev_b32_e32 v78, 16, v12
	v_and_b32_e32 v79, 0xffff0000, v12
	v_lshlrev_b32_e32 v80, 16, v13
	v_and_b32_e32 v81, 0xffff0000, v13
	v_lshlrev_b32_e32 v82, 16, v14
	v_and_b32_e32 v83, 0xffff0000, v14
	v_lshlrev_b32_e32 v84, 16, v15
	v_and_b32_e32 v85, 0xffff0000, v15
	v_lshlrev_b32_e32 v86, 16, v16
	v_and_b32_e32 v87, 0xffff0000, v16
	v_lshlrev_b32_e32 v88, 16, v17
	v_and_b32_e32 v89, 0xffff0000, v17
	v_lshlrev_b32_e32 v90, 16, v18
	v_and_b32_e32 v91, 0xffff0000, v18
	v_lshlrev_b32_e32 v92, 16, v19
	v_and_b32_e32 v93, 0xffff0000, v19
	v_pk_mul_f32 v[28:29], v[78:79], s[56:57]
	v_pk_mul_f32 v[30:31], v[80:81], s[56:57]
	v_pk_mul_f32 v[32:33], v[82:83], s[56:57]
	v_pk_mul_f32 v[34:35], v[84:85], s[56:57]
	v_pk_mul_f32 v[36:37], v[86:87], s[56:57]
	v_pk_mul_f32 v[38:39], v[88:89], s[56:57]
	v_pk_mul_f32 v[40:41], v[90:91], s[56:57]
	v_pk_mul_f32 v[42:43], v[92:93], s[56:57]
	v_exp_f32_e32 v28, v28
	v_exp_f32_e32 v29, v29
	v_exp_f32_e32 v30, v30
	v_exp_f32_e32 v31, v31
	v_exp_f32_e32 v32, v32
	v_exp_f32_e32 v33, v33
	v_exp_f32_e32 v34, v34
	v_exp_f32_e32 v35, v35
	v_exp_f32_e32 v36, v36
	v_exp_f32_e32 v37, v37
	v_exp_f32_e32 v38, v38
	v_exp_f32_e32 v39, v39
	v_exp_f32_e32 v40, v40
	v_exp_f32_e32 v41, v41
	v_exp_f32_e32 v42, v42
	v_exp_f32_e32 v43, v43
	v_pk_add_f32 v[28:29], v[28:29], s[54:55]
	v_pk_add_f32 v[30:31], v[30:31], s[54:55]
	v_pk_add_f32 v[32:33], v[32:33], s[54:55]
	v_pk_add_f32 v[34:35], v[34:35], s[54:55]
	v_pk_add_f32 v[36:37], v[36:37], s[54:55]
	v_pk_add_f32 v[38:39], v[38:39], s[54:55]
	v_pk_add_f32 v[40:41], v[40:41], s[54:55]
	v_pk_add_f32 v[42:43], v[42:43], s[54:55]
	v_rcp_f32_e32 v28, v28
	v_rcp_f32_e32 v29, v29
	v_rcp_f32_e32 v30, v30
	v_rcp_f32_e32 v31, v31
	v_rcp_f32_e32 v32, v32
	v_rcp_f32_e32 v33, v33
	v_rcp_f32_e32 v34, v34
	v_rcp_f32_e32 v35, v35
	v_rcp_f32_e32 v36, v36
	v_rcp_f32_e32 v37, v37
	v_rcp_f32_e32 v38, v38
	v_rcp_f32_e32 v39, v39
	v_rcp_f32_e32 v40, v40
	v_rcp_f32_e32 v41, v41
	v_rcp_f32_e32 v42, v42
	v_rcp_f32_e32 v43, v43
	v_pk_mul_f32 v[28:29], v[78:79], v[28:29]
	v_pk_mul_f32 v[30:31], v[80:81], v[30:31]
	v_pk_mul_f32 v[32:33], v[82:83], v[32:33]
	v_pk_mul_f32 v[34:35], v[84:85], v[34:35]
	v_pk_mul_f32 v[36:37], v[86:87], v[36:37]
	v_pk_mul_f32 v[38:39], v[88:89], v[38:39]
	v_pk_mul_f32 v[40:41], v[90:91], v[40:41]
	v_pk_mul_f32 v[42:43], v[92:93], v[42:43]
	v_pk_mul_f32 v[28:29], v[46:47], v[28:29]
	v_pk_mul_f32 v[30:31], v[48:49], v[30:31]
	v_pk_mul_f32 v[32:33], v[50:51], v[32:33]
	v_pk_mul_f32 v[34:35], v[52:53], v[34:35]
	v_pk_mul_f32 v[36:37], v[54:55], v[36:37]
	v_pk_mul_f32 v[38:39], v[56:57], v[38:39]
	v_pk_mul_f32 v[40:41], v[58:59], v[40:41]
	v_pk_mul_f32 v[42:43], v[60:61], v[42:43]
	v_cvt_pk_bf16_f32 v78, v28, v29
	v_cvt_pk_bf16_f32 v79, v30, v31
	v_cvt_pk_bf16_f32 v80, v32, v33
	v_cvt_pk_bf16_f32 v81, v34, v35
	v_cvt_pk_bf16_f32 v82, v36, v37
	v_cvt_pk_bf16_f32 v83, v38, v39
	v_cvt_pk_bf16_f32 v84, v40, v41
	v_cvt_pk_bf16_f32 v85, v42, v43
	global_store_dwordx2 v[4:5], v[78:79], off offset:0
	global_store_dwordx2 v[4:5], v[80:81], off offset:16
	global_store_dwordx2 v[4:5], v[82:83], off offset:32
	global_store_dwordx2 v[4:5], v[84:85], off offset:48
	v_lshlrev_b32_e32 v78, 16, v20
	v_and_b32_e32 v79, 0xffff0000, v20
	v_lshlrev_b32_e32 v80, 16, v21
	v_and_b32_e32 v81, 0xffff0000, v21
	v_lshlrev_b32_e32 v82, 16, v22
	v_and_b32_e32 v83, 0xffff0000, v22
	v_lshlrev_b32_e32 v84, 16, v23
	v_and_b32_e32 v85, 0xffff0000, v23
	v_lshlrev_b32_e32 v86, 16, v24
	v_and_b32_e32 v87, 0xffff0000, v24
	v_lshlrev_b32_e32 v88, 16, v25
	v_and_b32_e32 v89, 0xffff0000, v25
	v_lshlrev_b32_e32 v90, 16, v26
	v_and_b32_e32 v91, 0xffff0000, v26
	v_lshlrev_b32_e32 v92, 16, v27
	v_and_b32_e32 v93, 0xffff0000, v27
	v_pk_mul_f32 v[28:29], v[78:79], s[56:57]
	v_pk_mul_f32 v[30:31], v[80:81], s[56:57]
	v_pk_mul_f32 v[32:33], v[82:83], s[56:57]
	v_pk_mul_f32 v[34:35], v[84:85], s[56:57]
	v_pk_mul_f32 v[36:37], v[86:87], s[56:57]
	v_pk_mul_f32 v[38:39], v[88:89], s[56:57]
	v_pk_mul_f32 v[40:41], v[90:91], s[56:57]
	v_pk_mul_f32 v[42:43], v[92:93], s[56:57]
	v_exp_f32_e32 v28, v28
	v_exp_f32_e32 v29, v29
	v_exp_f32_e32 v30, v30
	v_exp_f32_e32 v31, v31
	v_exp_f32_e32 v32, v32
	v_exp_f32_e32 v33, v33
	v_exp_f32_e32 v34, v34
	v_exp_f32_e32 v35, v35
	v_exp_f32_e32 v36, v36
	v_exp_f32_e32 v37, v37
	v_exp_f32_e32 v38, v38
	v_exp_f32_e32 v39, v39
	v_exp_f32_e32 v40, v40
	v_exp_f32_e32 v41, v41
	v_exp_f32_e32 v42, v42
	v_exp_f32_e32 v43, v43
	v_pk_add_f32 v[28:29], v[28:29], s[54:55]
	v_pk_add_f32 v[30:31], v[30:31], s[54:55]
	v_pk_add_f32 v[32:33], v[32:33], s[54:55]
	v_pk_add_f32 v[34:35], v[34:35], s[54:55]
	v_pk_add_f32 v[36:37], v[36:37], s[54:55]
	v_pk_add_f32 v[38:39], v[38:39], s[54:55]
	v_pk_add_f32 v[40:41], v[40:41], s[54:55]
	v_pk_add_f32 v[42:43], v[42:43], s[54:55]
	v_rcp_f32_e32 v28, v28
	v_rcp_f32_e32 v29, v29
	v_rcp_f32_e32 v30, v30
	v_rcp_f32_e32 v31, v31
	v_rcp_f32_e32 v32, v32
	v_rcp_f32_e32 v33, v33
	v_rcp_f32_e32 v34, v34
	v_rcp_f32_e32 v35, v35
	v_rcp_f32_e32 v36, v36
	v_rcp_f32_e32 v37, v37
	v_rcp_f32_e32 v38, v38
	v_rcp_f32_e32 v39, v39
	v_rcp_f32_e32 v40, v40
	v_rcp_f32_e32 v41, v41
	v_rcp_f32_e32 v42, v42
	v_rcp_f32_e32 v43, v43
	v_pk_mul_f32 v[28:29], v[78:79], v[28:29]
	v_pk_mul_f32 v[30:31], v[80:81], v[30:31]
	v_pk_mul_f32 v[32:33], v[82:83], v[32:33]
	v_pk_mul_f32 v[34:35], v[84:85], v[34:35]
	v_pk_mul_f32 v[36:37], v[86:87], v[36:37]
	v_pk_mul_f32 v[38:39], v[88:89], v[38:39]
	v_pk_mul_f32 v[40:41], v[90:91], v[40:41]
	v_pk_mul_f32 v[42:43], v[92:93], v[42:43]
	v_pk_mul_f32 v[28:29], v[62:63], v[28:29]
	v_pk_mul_f32 v[30:31], v[64:65], v[30:31]
	v_pk_mul_f32 v[32:33], v[66:67], v[32:33]
	v_pk_mul_f32 v[34:35], v[68:69], v[34:35]
	v_pk_mul_f32 v[36:37], v[70:71], v[36:37]
	v_pk_mul_f32 v[38:39], v[72:73], v[38:39]
	v_pk_mul_f32 v[40:41], v[74:75], v[40:41]
	v_pk_mul_f32 v[42:43], v[76:77], v[42:43]
	v_cvt_pk_bf16_f32 v78, v28, v29
	v_cvt_pk_bf16_f32 v79, v30, v31
	v_cvt_pk_bf16_f32 v80, v32, v33
	v_cvt_pk_bf16_f32 v81, v34, v35
	v_cvt_pk_bf16_f32 v82, v36, v37
	v_cvt_pk_bf16_f32 v83, v38, v39
	v_cvt_pk_bf16_f32 v84, v40, v41
	v_cvt_pk_bf16_f32 v85, v42, v43
	global_store_dwordx2 v[4:5], v[78:79], off offset:64
	global_store_dwordx2 v[4:5], v[80:81], off offset:80
	global_store_dwordx2 v[4:5], v[82:83], off offset:96
	global_store_dwordx2 v[4:5], v[84:85], off offset:112
	v_lshl_add_u64 v[4:5], s[52:53], 0, v[10:11]
	global_load_dwordx2 v[12:13], v[4:5], off offset:128
	global_load_dwordx2 v[14:15], v[4:5], off offset:144
	global_load_dwordx2 v[16:17], v[4:5], off offset:160
	global_load_dwordx2 v[18:19], v[4:5], off offset:176
	global_load_dwordx2 v[20:21], v[4:5], off offset:192
	global_load_dwordx2 v[22:23], v[4:5], off offset:208
	global_load_dwordx2 v[24:25], v[4:5], off offset:224
	global_load_dwordx2 v[26:27], v[4:5], off offset:240
	s_waitcnt vmcnt(8)
	s_barrier
	s_add_u32 s46, s44, 0x100
	s_addc_u32 s47, s45, 0
	s_add_i32 s43, s48, 0x0
	v_lshl_add_u64 v[4:5], s[46:47], 0, v[6:7]
	s_mov_b32 m0, s43
	s_nop 0
	global_load_lds_dwordx4 v[4:5], off
	s_add_u32 s46, s44, 0x8100
	s_addc_u32 s47, s45, 0
	s_add_i32 s43, s48, 0x2000
	v_lshl_add_u64 v[4:5], s[46:47], 0, v[6:7]
	s_mov_b32 m0, s43
	s_nop 0
	global_load_lds_dwordx4 v[4:5], off
	s_add_u32 s46, s44, 0x10100
	s_addc_u32 s47, s45, 0
	s_add_i32 s43, s48, 0x4000
	v_lshl_add_u64 v[4:5], s[46:47], 0, v[6:7]
	s_mov_b32 m0, s43
	s_nop 0
	global_load_lds_dwordx4 v[4:5], off
	s_add_u32 s46, s44, 0x18100
	s_addc_u32 s47, s45, 0
	s_add_i32 s43, s48, 0x6000
	v_lshl_add_u64 v[4:5], s[46:47], 0, v[6:7]
	s_mov_b32 m0, s43
	s_nop 0
	global_load_lds_dwordx4 v[4:5], off
	s_cmp_lt_u32 s41, 2
	s_cbranch_scc0 .Lpool_xdma_done2
	s_add_u32 s46, s44, 0x20100
	s_addc_u32 s47, s45, 0
	s_add_i32 s43, s48, 0x8000
	v_lshl_add_u64 v[4:5], s[46:47], 0, v[6:7]
	s_mov_b32 m0, s43
	s_nop 0
	global_load_lds_dwordx4 v[4:5], off
.Lpool_xdma_done2:
	v_readlane_b32 s54, v250, 27
	v_readlane_b32 s55, v250, 28
	v_mov_b32_e32 v2, v45
	v_mov_b32_e32 v3, 0
	s_add_i32 s43, s48, 0x1a000
	v_lshl_add_u64 v[4:5], s[54:55], 0, v[2:3]
	s_mov_b32 m0, s43
	s_nop 0
	global_load_lds_dwordx4 v[4:5], off
	ds_read_u16 v58, v8 offset:36352
	ds_read_u16 v59, v8 offset:36480
	ds_read_u16 v60, v8 offset:36608
	ds_read_u16 v61, v8 offset:36736
	ds_read_u16 v62, v8 offset:36864
	ds_read_u16 v63, v8 offset:36992
	ds_read_u16 v64, v8 offset:37120
	ds_read_u16 v65, v8 offset:37248
	ds_read_u16 v66, v8 offset:37376
	ds_read_u16 v67, v8 offset:37504
	ds_read_u16 v68, v8 offset:37632
	ds_read_u16 v69, v8 offset:37760
	ds_read_u16 v70, v8 offset:37888
	ds_read_u16 v71, v8 offset:38016
	ds_read_u16 v72, v8 offset:38144
	ds_read_u16 v73, v8 offset:38272
	ds_read_u16 v74, v8 offset:38400
	ds_read_u16 v75, v8 offset:38528
	ds_read_u16 v76, v8 offset:38656
	ds_read_u16 v77, v8 offset:38784
	ds_read_u16 v78, v8 offset:38912
	ds_read_u16 v79, v8 offset:39040
	ds_read_u16 v80, v8 offset:39168
	ds_read_u16 v81, v8 offset:39296
	ds_read_u16 v82, v8 offset:39424
	ds_read_u16 v83, v8 offset:39552
	ds_read_u16 v84, v8 offset:39680
	ds_read_u16 v85, v8 offset:39808
	ds_read_u16 v86, v8 offset:39936
	ds_read_u16 v87, v8 offset:40064
	ds_read_u16 v88, v8 offset:40192
	ds_read_u16 v89, v8 offset:40320
	ds_read_u16 v90, v8 offset:40448
	ds_read_u16 v91, v8 offset:40576
	ds_read_u16 v92, v8 offset:40704
	s_mov_b32 s50, 0x3e800000
	s_waitcnt lgkmcnt(0)
	v_lshlrev_b32_e32 v58, 16, v58
	v_lshlrev_b32_e32 v59, 16, v59
	v_lshlrev_b32_e32 v60, 16, v60
	v_lshlrev_b32_e32 v61, 16, v61
	v_lshlrev_b32_e32 v62, 16, v62
	v_lshlrev_b32_e32 v63, 16, v63
	v_lshlrev_b32_e32 v64, 16, v64
	v_lshlrev_b32_e32 v65, 16, v65
	v_lshlrev_b32_e32 v66, 16, v66
	v_lshlrev_b32_e32 v67, 16, v67
	v_lshlrev_b32_e32 v68, 16, v68
	v_lshlrev_b32_e32 v69, 16, v69
	v_lshlrev_b32_e32 v70, 16, v70
	v_lshlrev_b32_e32 v71, 16, v71
	v_lshlrev_b32_e32 v72, 16, v72
	v_lshlrev_b32_e32 v73, 16, v73
	v_lshlrev_b32_e32 v74, 16, v74
	v_lshlrev_b32_e32 v75, 16, v75
	v_lshlrev_b32_e32 v76, 16, v76
	v_lshlrev_b32_e32 v77, 16, v77
	v_lshlrev_b32_e32 v78, 16, v78
	v_lshlrev_b32_e32 v79, 16, v79
	v_lshlrev_b32_e32 v80, 16, v80
	v_lshlrev_b32_e32 v81, 16, v81
	v_lshlrev_b32_e32 v82, 16, v82
	v_lshlrev_b32_e32 v83, 16, v83
	v_lshlrev_b32_e32 v84, 16, v84
	v_lshlrev_b32_e32 v85, 16, v85
	v_lshlrev_b32_e32 v86, 16, v86
	v_lshlrev_b32_e32 v87, 16, v87
	v_lshlrev_b32_e32 v88, 16, v88
	v_lshlrev_b32_e32 v89, 16, v89
	v_lshlrev_b32_e32 v90, 16, v90
	v_lshlrev_b32_e32 v91, 16, v91
	v_lshlrev_b32_e32 v92, 16, v92
	s_cmp_eq_u32 s42, 1
	s_cbranch_scc0 .Lpool_nz1
	v_mov_b32_e32 v60, 0
	v_mov_b32_e32 v59, 0
	v_mov_b32_e32 v58, 0
.Lpool_nz1:
	v_add_f32_e32 v93, v61, v60
	v_add_f32_e32 v93, v93, v59
	v_add_f32_e32 v93, v93, v58
	s_cmp_eq_u32 s42, 1
	s_cselect_b32 s51, 0x3f800000, s50
	v_fma_f32 v2, v93, s51, -v61
	v_add_f32_e32 v93, v93, v62
	v_sub_f32_e32 v93, v93, v58
	s_cmp_eq_u32 s42, 1
	s_cselect_b32 s51, 0x3f000000, s50
	v_fma_f32 v3, v93, s51, -v62
	v_cvt_pk_bf16_f32 v2, v2, v3
	ds_write_b16 v9, v2 offset:0
	ds_write_b16_d16_hi v9, v2 offset:144
	v_add_f32_e32 v93, v93, v63
	v_sub_f32_e32 v93, v93, v59
	s_cmp_eq_u32 s42, 1
	s_cselect_b32 s51, 0x3eaaaaab, s50
	v_fma_f32 v4, v93, s51, -v63
	v_add_f32_e32 v93, v93, v64
	v_sub_f32_e32 v93, v93, v60
	v_fma_f32 v5, v93, s50, -v64
	v_cvt_pk_bf16_f32 v4, v4, v5
	ds_write_b16 v9, v4 offset:288
	ds_write_b16_d16_hi v9, v4 offset:432
	v_add_f32_e32 v93, v93, v65
	v_sub_f32_e32 v93, v93, v61
	v_fma_f32 v2, v93, s50, -v65
	v_add_f32_e32 v93, v93, v66
	v_sub_f32_e32 v93, v93, v62
	v_fma_f32 v3, v93, s50, -v66
	v_cvt_pk_bf16_f32 v2, v2, v3
	ds_write_b16 v9, v2 offset:576
	ds_write_b16_d16_hi v9, v2 offset:720
	v_add_f32_e32 v93, v93, v67
	v_sub_f32_e32 v93, v93, v63
	v_fma_f32 v4, v93, s50, -v67
	v_add_f32_e32 v93, v93, v68
	v_sub_f32_e32 v93, v93, v64
	v_fma_f32 v5, v93, s50, -v68
	v_cvt_pk_bf16_f32 v4, v4, v5
	ds_write_b16 v9, v4 offset:864
	ds_write_b16_d16_hi v9, v4 offset:1008
	v_add_f32_e32 v93, v93, v69
	v_sub_f32_e32 v93, v93, v65
	v_fma_f32 v2, v93, s50, -v69
	v_add_f32_e32 v93, v93, v70
	v_sub_f32_e32 v93, v93, v66
	v_fma_f32 v3, v93, s50, -v70
	v_cvt_pk_bf16_f32 v2, v2, v3
	ds_write_b16 v9, v2 offset:1152
	ds_write_b16_d16_hi v9, v2 offset:1296
	v_add_f32_e32 v93, v93, v71
	v_sub_f32_e32 v93, v93, v67
	v_fma_f32 v4, v93, s50, -v71
	v_add_f32_e32 v93, v93, v72
	v_sub_f32_e32 v93, v93, v68
	v_fma_f32 v5, v93, s50, -v72
	v_cvt_pk_bf16_f32 v4, v4, v5
	ds_write_b16 v9, v4 offset:1440
	ds_write_b16_d16_hi v9, v4 offset:1584
	v_add_f32_e32 v93, v93, v73
	v_sub_f32_e32 v93, v93, v69
	v_fma_f32 v2, v93, s50, -v73
	v_add_f32_e32 v93, v93, v74
	v_sub_f32_e32 v93, v93, v70
	v_fma_f32 v3, v93, s50, -v74
	v_cvt_pk_bf16_f32 v2, v2, v3
	ds_write_b16 v9, v2 offset:1728
	ds_write_b16_d16_hi v9, v2 offset:1872
	v_add_f32_e32 v93, v93, v75
	v_sub_f32_e32 v93, v93, v71
	v_fma_f32 v4, v93, s50, -v75
	v_add_f32_e32 v93, v93, v76
	v_sub_f32_e32 v93, v93, v72
	v_fma_f32 v5, v93, s50, -v76
	v_cvt_pk_bf16_f32 v4, v4, v5
	ds_write_b16 v9, v4 offset:2016
	ds_write_b16_d16_hi v9, v4 offset:2160
	v_add_f32_e32 v93, v93, v77
	v_sub_f32_e32 v93, v93, v73
	v_fma_f32 v2, v93, s50, -v77
	v_add_f32_e32 v93, v93, v78
	v_sub_f32_e32 v93, v93, v74
	v_fma_f32 v3, v93, s50, -v78
	v_cvt_pk_bf16_f32 v2, v2, v3
	ds_write_b16 v9, v2 offset:2304
	ds_write_b16_d16_hi v9, v2 offset:2448
	v_add_f32_e32 v93, v93, v79
	v_sub_f32_e32 v93, v93, v75
	v_fma_f32 v4, v93, s50, -v79
	v_add_f32_e32 v93, v93, v80
	v_sub_f32_e32 v93, v93, v76
	v_fma_f32 v5, v93, s50, -v80
	v_cvt_pk_bf16_f32 v4, v4, v5
	ds_write_b16 v9, v4 offset:2592
	ds_write_b16_d16_hi v9, v4 offset:2736
	v_add_f32_e32 v93, v93, v81
	v_sub_f32_e32 v93, v93, v77
	v_fma_f32 v2, v93, s50, -v81
	v_add_f32_e32 v93, v93, v82
	v_sub_f32_e32 v93, v93, v78
	v_fma_f32 v3, v93, s50, -v82
	v_cvt_pk_bf16_f32 v2, v2, v3
	ds_write_b16 v9, v2 offset:2880
	ds_write_b16_d16_hi v9, v2 offset:3024
	v_add_f32_e32 v93, v93, v83
	v_sub_f32_e32 v93, v93, v79
	v_fma_f32 v4, v93, s50, -v83
	v_add_f32_e32 v93, v93, v84
	v_sub_f32_e32 v93, v93, v80
	v_fma_f32 v5, v93, s50, -v84
	v_cvt_pk_bf16_f32 v4, v4, v5
	ds_write_b16 v9, v4 offset:3168
	ds_write_b16_d16_hi v9, v4 offset:3312
	v_add_f32_e32 v93, v93, v85
	v_sub_f32_e32 v93, v93, v81
	v_fma_f32 v2, v93, s50, -v85
	v_add_f32_e32 v93, v93, v86
	v_sub_f32_e32 v93, v93, v82
	v_fma_f32 v3, v93, s50, -v86
	v_cvt_pk_bf16_f32 v2, v2, v3
	ds_write_b16 v9, v2 offset:3456
	ds_write_b16_d16_hi v9, v2 offset:3600
	v_add_f32_e32 v93, v93, v87
	v_sub_f32_e32 v93, v93, v83
	v_fma_f32 v4, v93, s50, -v87
	v_add_f32_e32 v93, v93, v88
	v_sub_f32_e32 v93, v93, v84
	v_fma_f32 v5, v93, s50, -v88
	v_cvt_pk_bf16_f32 v4, v4, v5
	ds_write_b16 v9, v4 offset:3744
	ds_write_b16_d16_hi v9, v4 offset:3888
	v_add_f32_e32 v93, v93, v89
	v_sub_f32_e32 v93, v93, v85
	v_fma_f32 v2, v93, s50, -v89
	v_add_f32_e32 v93, v93, v90
	v_sub_f32_e32 v93, v93, v86
	v_fma_f32 v3, v93, s50, -v90
	v_cvt_pk_bf16_f32 v2, v2, v3
	ds_write_b16 v9, v2 offset:4032
	ds_write_b16_d16_hi v9, v2 offset:4176
	v_add_f32_e32 v93, v93, v91
	v_sub_f32_e32 v93, v93, v87
	v_fma_f32 v4, v93, s50, -v91
	v_add_f32_e32 v93, v93, v92
	v_sub_f32_e32 v93, v93, v88
	v_fma_f32 v5, v93, s50, -v92
	v_cvt_pk_bf16_f32 v4, v4, v5
	ds_write_b16 v9, v4 offset:4320
	ds_write_b16_d16_hi v9, v4 offset:4464
	v_and_b32_e32 v2, 31, v0
	v_lshrrev_b32_e32 v3, 5, v0
	v_bfe_u32 v4, v0, 1, 3
	v_xor_b32_e32 v3, v3, v4
	v_lshlrev_b32_e32 v2, 7, v2
	v_add_u32_e32 v2, 0x1c000, v2
	v_lshl_add_u32 v5, v3, 4, v2
	v_xor_b32_e32 v4, 2, v3
	v_lshl_add_u32 v4, v4, 4, v2
	v_xor_b32_e32 v88, 4, v3
	v_xor_b32_e32 v3, 6, v3
	v_lshl_add_u32 v3, v3, 4, v2
	v_lshl_add_u32 v2, v88, 4, v2
	s_waitcnt lgkmcnt(0)
	ds_read_b128 v[28:31], v5 offset:0
	ds_read_b128 v[32:35], v5 offset:4096
	ds_read_b128 v[78:81], v44 offset:0
	ds_read_b128 v[82:85], v44 offset:32
	ds_read_b128 v[86:89], v44 offset:64
	ds_read_b128 v[90:93], v44 offset:96
	ds_read_b128 v[36:39], v4 offset:0
	ds_read_b128 v[40:43], v4 offset:4096
	s_waitcnt lgkmcnt(0)
	v_mfma_f32_32x32x16_bf16 v[46:61], v[28:31], v[78:81], 0
	v_mfma_f32_32x32x16_bf16 v[62:77], v[32:35], v[78:81], 0
	ds_read_b128 v[28:31], v2 offset:0
	ds_read_b128 v[32:35], v2 offset:4096
	v_mfma_f32_32x32x16_bf16 v[46:61], v[36:39], v[82:85], v[46:61]
	v_mfma_f32_32x32x16_bf16 v[62:77], v[40:43], v[82:85], v[62:77]
	ds_read_b128 v[36:39], v3 offset:0
	ds_read_b128 v[40:43], v3 offset:4096
	s_waitcnt lgkmcnt(2)
	v_mfma_f32_32x32x16_bf16 v[46:61], v[28:31], v[86:89], v[46:61]
	v_mfma_f32_32x32x16_bf16 v[62:77], v[32:35], v[86:89], v[62:77]
	s_waitcnt lgkmcnt(0)
	v_mfma_f32_32x32x16_bf16 v[46:61], v[36:39], v[90:93], v[46:61]
	v_mfma_f32_32x32x16_bf16 v[62:77], v[40:43], v[90:93], v[62:77]
	v_lshl_add_u64 v[4:5], s[52:53], 0, v[10:11]
	s_nop 14
	s_waitcnt vmcnt(5)
	s_mov_b32 s56, 0xbfb8aa3b
	s_mov_b32 s57, 0xbfb8aa3b
	s_mov_b32 s54, 1.0
	s_mov_b32 s55, 1.0
	v_lshlrev_b32_e32 v78, 16, v12
	v_and_b32_e32 v79, 0xffff0000, v12
	v_lshlrev_b32_e32 v80, 16, v13
	v_and_b32_e32 v81, 0xffff0000, v13
	v_lshlrev_b32_e32 v82, 16, v14
	v_and_b32_e32 v83, 0xffff0000, v14
	v_lshlrev_b32_e32 v84, 16, v15
	v_and_b32_e32 v85, 0xffff0000, v15
	v_lshlrev_b32_e32 v86, 16, v16
	v_and_b32_e32 v87, 0xffff0000, v16
	v_lshlrev_b32_e32 v88, 16, v17
	v_and_b32_e32 v89, 0xffff0000, v17
	v_lshlrev_b32_e32 v90, 16, v18
	v_and_b32_e32 v91, 0xffff0000, v18
	v_lshlrev_b32_e32 v92, 16, v19
	v_and_b32_e32 v93, 0xffff0000, v19
	v_pk_mul_f32 v[28:29], v[78:79], s[56:57]
	v_pk_mul_f32 v[30:31], v[80:81], s[56:57]
	v_pk_mul_f32 v[32:33], v[82:83], s[56:57]
	v_pk_mul_f32 v[34:35], v[84:85], s[56:57]
	v_pk_mul_f32 v[36:37], v[86:87], s[56:57]
	v_pk_mul_f32 v[38:39], v[88:89], s[56:57]
	v_pk_mul_f32 v[40:41], v[90:91], s[56:57]
	v_pk_mul_f32 v[42:43], v[92:93], s[56:57]
	v_exp_f32_e32 v28, v28
	v_exp_f32_e32 v29, v29
	v_exp_f32_e32 v30, v30
	v_exp_f32_e32 v31, v31
	v_exp_f32_e32 v32, v32
	v_exp_f32_e32 v33, v33
	v_exp_f32_e32 v34, v34
	v_exp_f32_e32 v35, v35
	v_exp_f32_e32 v36, v36
	v_exp_f32_e32 v37, v37
	v_exp_f32_e32 v38, v38
	v_exp_f32_e32 v39, v39
	v_exp_f32_e32 v40, v40
	v_exp_f32_e32 v41, v41
	v_exp_f32_e32 v42, v42
	v_exp_f32_e32 v43, v43
	v_pk_add_f32 v[28:29], v[28:29], s[54:55]
	v_pk_add_f32 v[30:31], v[30:31], s[54:55]
	v_pk_add_f32 v[32:33], v[32:33], s[54:55]
	v_pk_add_f32 v[34:35], v[34:35], s[54:55]
	v_pk_add_f32 v[36:37], v[36:37], s[54:55]
	v_pk_add_f32 v[38:39], v[38:39], s[54:55]
	v_pk_add_f32 v[40:41], v[40:41], s[54:55]
	v_pk_add_f32 v[42:43], v[42:43], s[54:55]
	v_rcp_f32_e32 v28, v28
	v_rcp_f32_e32 v29, v29
	v_rcp_f32_e32 v30, v30
	v_rcp_f32_e32 v31, v31
	v_rcp_f32_e32 v32, v32
	v_rcp_f32_e32 v33, v33
	v_rcp_f32_e32 v34, v34
	v_rcp_f32_e32 v35, v35
	v_rcp_f32_e32 v36, v36
	v_rcp_f32_e32 v37, v37
	v_rcp_f32_e32 v38, v38
	v_rcp_f32_e32 v39, v39
	v_rcp_f32_e32 v40, v40
	v_rcp_f32_e32 v41, v41
	v_rcp_f32_e32 v42, v42
	v_rcp_f32_e32 v43, v43
	v_pk_mul_f32 v[28:29], v[78:79], v[28:29]
	v_pk_mul_f32 v[30:31], v[80:81], v[30:31]
	v_pk_mul_f32 v[32:33], v[82:83], v[32:33]
	v_pk_mul_f32 v[34:35], v[84:85], v[34:35]
	v_pk_mul_f32 v[36:37], v[86:87], v[36:37]
	v_pk_mul_f32 v[38:39], v[88:89], v[38:39]
	v_pk_mul_f32 v[40:41], v[90:91], v[40:41]
	v_pk_mul_f32 v[42:43], v[92:93], v[42:43]
	v_pk_mul_f32 v[28:29], v[46:47], v[28:29]
	v_pk_mul_f32 v[30:31], v[48:49], v[30:31]
	v_pk_mul_f32 v[32:33], v[50:51], v[32:33]
	v_pk_mul_f32 v[34:35], v[52:53], v[34:35]
	v_pk_mul_f32 v[36:37], v[54:55], v[36:37]
	v_pk_mul_f32 v[38:39], v[56:57], v[38:39]
	v_pk_mul_f32 v[40:41], v[58:59], v[40:41]
	v_pk_mul_f32 v[42:43], v[60:61], v[42:43]
	v_cvt_pk_bf16_f32 v78, v28, v29
	v_cvt_pk_bf16_f32 v79, v30, v31
	v_cvt_pk_bf16_f32 v80, v32, v33
	v_cvt_pk_bf16_f32 v81, v34, v35
	v_cvt_pk_bf16_f32 v82, v36, v37
	v_cvt_pk_bf16_f32 v83, v38, v39
	v_cvt_pk_bf16_f32 v84, v40, v41
	v_cvt_pk_bf16_f32 v85, v42, v43
	global_store_dwordx2 v[4:5], v[78:79], off offset:128
	global_store_dwordx2 v[4:5], v[80:81], off offset:144
	global_store_dwordx2 v[4:5], v[82:83], off offset:160
	global_store_dwordx2 v[4:5], v[84:85], off offset:176
	v_lshlrev_b32_e32 v78, 16, v20
	v_and_b32_e32 v79, 0xffff0000, v20
	v_lshlrev_b32_e32 v80, 16, v21
	v_and_b32_e32 v81, 0xffff0000, v21
	v_lshlrev_b32_e32 v82, 16, v22
	v_and_b32_e32 v83, 0xffff0000, v22
	v_lshlrev_b32_e32 v84, 16, v23
	v_and_b32_e32 v85, 0xffff0000, v23
	v_lshlrev_b32_e32 v86, 16, v24
	v_and_b32_e32 v87, 0xffff0000, v24
	v_lshlrev_b32_e32 v88, 16, v25
	v_and_b32_e32 v89, 0xffff0000, v25
	v_lshlrev_b32_e32 v90, 16, v26
	v_and_b32_e32 v91, 0xffff0000, v26
	v_lshlrev_b32_e32 v92, 16, v27
	v_and_b32_e32 v93, 0xffff0000, v27
	v_pk_mul_f32 v[28:29], v[78:79], s[56:57]
	v_pk_mul_f32 v[30:31], v[80:81], s[56:57]
	v_pk_mul_f32 v[32:33], v[82:83], s[56:57]
	v_pk_mul_f32 v[34:35], v[84:85], s[56:57]
	v_pk_mul_f32 v[36:37], v[86:87], s[56:57]
	v_pk_mul_f32 v[38:39], v[88:89], s[56:57]
	v_pk_mul_f32 v[40:41], v[90:91], s[56:57]
	v_pk_mul_f32 v[42:43], v[92:93], s[56:57]
	v_exp_f32_e32 v28, v28
	v_exp_f32_e32 v29, v29
	v_exp_f32_e32 v30, v30
	v_exp_f32_e32 v31, v31
	v_exp_f32_e32 v32, v32
	v_exp_f32_e32 v33, v33
	v_exp_f32_e32 v34, v34
	v_exp_f32_e32 v35, v35
	v_exp_f32_e32 v36, v36
	v_exp_f32_e32 v37, v37
	v_exp_f32_e32 v38, v38
	v_exp_f32_e32 v39, v39
	v_exp_f32_e32 v40, v40
	v_exp_f32_e32 v41, v41
	v_exp_f32_e32 v42, v42
	v_exp_f32_e32 v43, v43
	v_pk_add_f32 v[28:29], v[28:29], s[54:55]
	v_pk_add_f32 v[30:31], v[30:31], s[54:55]
	v_pk_add_f32 v[32:33], v[32:33], s[54:55]
	v_pk_add_f32 v[34:35], v[34:35], s[54:55]
	v_pk_add_f32 v[36:37], v[36:37], s[54:55]
	v_pk_add_f32 v[38:39], v[38:39], s[54:55]
	v_pk_add_f32 v[40:41], v[40:41], s[54:55]
	v_pk_add_f32 v[42:43], v[42:43], s[54:55]
	v_rcp_f32_e32 v28, v28
	v_rcp_f32_e32 v29, v29
	v_rcp_f32_e32 v30, v30
	v_rcp_f32_e32 v31, v31
	v_rcp_f32_e32 v32, v32
	v_rcp_f32_e32 v33, v33
	v_rcp_f32_e32 v34, v34
	v_rcp_f32_e32 v35, v35
	v_rcp_f32_e32 v36, v36
	v_rcp_f32_e32 v37, v37
	v_rcp_f32_e32 v38, v38
	v_rcp_f32_e32 v39, v39
	v_rcp_f32_e32 v40, v40
	v_rcp_f32_e32 v41, v41
	v_rcp_f32_e32 v42, v42
	v_rcp_f32_e32 v43, v43
	v_pk_mul_f32 v[28:29], v[78:79], v[28:29]
	v_pk_mul_f32 v[30:31], v[80:81], v[30:31]
	v_pk_mul_f32 v[32:33], v[82:83], v[32:33]
	v_pk_mul_f32 v[34:35], v[84:85], v[34:35]
	v_pk_mul_f32 v[36:37], v[86:87], v[36:37]
	v_pk_mul_f32 v[38:39], v[88:89], v[38:39]
	v_pk_mul_f32 v[40:41], v[90:91], v[40:41]
	v_pk_mul_f32 v[42:43], v[92:93], v[42:43]
	v_pk_mul_f32 v[28:29], v[62:63], v[28:29]
	v_pk_mul_f32 v[30:31], v[64:65], v[30:31]
	v_pk_mul_f32 v[32:33], v[66:67], v[32:33]
	v_pk_mul_f32 v[34:35], v[68:69], v[34:35]
	v_pk_mul_f32 v[36:37], v[70:71], v[36:37]
	v_pk_mul_f32 v[38:39], v[72:73], v[38:39]
	v_pk_mul_f32 v[40:41], v[74:75], v[40:41]
	v_pk_mul_f32 v[42:43], v[76:77], v[42:43]
	v_cvt_pk_bf16_f32 v78, v28, v29
	v_cvt_pk_bf16_f32 v79, v30, v31
	v_cvt_pk_bf16_f32 v80, v32, v33
	v_cvt_pk_bf16_f32 v81, v34, v35
	v_cvt_pk_bf16_f32 v82, v36, v37
	v_cvt_pk_bf16_f32 v83, v38, v39
	v_cvt_pk_bf16_f32 v84, v40, v41
	v_cvt_pk_bf16_f32 v85, v42, v43
	global_store_dwordx2 v[4:5], v[78:79], off offset:192
	global_store_dwordx2 v[4:5], v[80:81], off offset:208
	global_store_dwordx2 v[4:5], v[82:83], off offset:224
	global_store_dwordx2 v[4:5], v[84:85], off offset:240
	v_lshl_add_u64 v[4:5], s[52:53], 0, v[10:11]
	global_load_dwordx2 v[12:13], v[4:5], off offset:256
	global_load_dwordx2 v[14:15], v[4:5], off offset:272
	global_load_dwordx2 v[16:17], v[4:5], off offset:288
	global_load_dwordx2 v[18:19], v[4:5], off offset:304
	global_load_dwordx2 v[20:21], v[4:5], off offset:320
	global_load_dwordx2 v[22:23], v[4:5], off offset:336
	global_load_dwordx2 v[24:25], v[4:5], off offset:352
	global_load_dwordx2 v[26:27], v[4:5], off offset:368
	s_waitcnt vmcnt(8)
	s_barrier
	s_add_u32 s46, s44, 0x180
	s_addc_u32 s47, s45, 0
	s_add_i32 s43, s48, 0x8800
	v_lshl_add_u64 v[4:5], s[46:47], 0, v[6:7]
	s_mov_b32 m0, s43
	s_nop 0
	global_load_lds_dwordx4 v[4:5], off
	s_add_u32 s46, s44, 0x8180
	s_addc_u32 s47, s45, 0
	s_add_i32 s43, s48, 0xa800
	v_lshl_add_u64 v[4:5], s[46:47], 0, v[6:7]
	s_mov_b32 m0, s43
	s_nop 0
	global_load_lds_dwordx4 v[4:5], off
	s_add_u32 s46, s44, 0x10180
	s_addc_u32 s47, s45, 0
	s_add_i32 s43, s48, 0xc800
	v_lshl_add_u64 v[4:5], s[46:47], 0, v[6:7]
	s_mov_b32 m0, s43
	s_nop 0
	global_load_lds_dwordx4 v[4:5], off
	s_add_u32 s46, s44, 0x18180
	s_addc_u32 s47, s45, 0
	s_add_i32 s43, s48, 0xe800
	v_lshl_add_u64 v[4:5], s[46:47], 0, v[6:7]
	s_mov_b32 m0, s43
	s_nop 0
	global_load_lds_dwordx4 v[4:5], off
	s_cmp_lt_u32 s41, 2
	s_cbranch_scc0 .Lpool_xdma_done3
	s_add_u32 s46, s44, 0x20180
	s_addc_u32 s47, s45, 0
	s_add_i32 s43, s48, 0x10800
	v_lshl_add_u64 v[4:5], s[46:47], 0, v[6:7]
	s_mov_b32 m0, s43
	s_nop 0
	global_load_lds_dwordx4 v[4:5], off
.Lpool_xdma_done3:
	v_readlane_b32 s54, v250, 29
	v_readlane_b32 s55, v250, 30
	v_mov_b32_e32 v2, v45
	v_mov_b32_e32 v3, 0
	s_add_i32 s43, s48, 0x1c000
	v_lshl_add_u64 v[4:5], s[54:55], 0, v[2:3]
	s_mov_b32 m0, s43
	s_nop 0
	global_load_lds_dwordx4 v[4:5], off
	ds_read_u16 v54, v8 offset:1024
	ds_read_u16 v55, v8 offset:1152
	ds_read_u16 v56, v8 offset:1280
	ds_read_u16 v57, v8 offset:1408
	ds_read_u16 v58, v8 offset:1536
	ds_read_u16 v59, v8 offset:1664
	ds_read_u16 v60, v8 offset:1792
	ds_read_u16 v61, v8 offset:1920
	ds_read_u16 v62, v8 offset:2048
	ds_read_u16 v63, v8 offset:2176
	ds_read_u16 v64, v8 offset:2304
	ds_read_u16 v65, v8 offset:2432
	ds_read_u16 v66, v8 offset:2560
	ds_read_u16 v67, v8 offset:2688
	ds_read_u16 v68, v8 offset:2816
	ds_read_u16 v69, v8 offset:2944
	ds_read_u16 v70, v8 offset:3072
	ds_read_u16 v71, v8 offset:3200
	ds_read_u16 v72, v8 offset:3328
	ds_read_u16 v73, v8 offset:3456
	ds_read_u16 v74, v8 offset:3584
	ds_read_u16 v75, v8 offset:3712
	ds_read_u16 v76, v8 offset:3840
	ds_read_u16 v77, v8 offset:3968
	ds_read_u16 v78, v8 offset:4096
	ds_read_u16 v79, v8 offset:4224
	ds_read_u16 v80, v8 offset:4352
	ds_read_u16 v81, v8 offset:4480
	ds_read_u16 v82, v8 offset:4608
	ds_read_u16 v83, v8 offset:4736
	ds_read_u16 v84, v8 offset:4864
	ds_read_u16 v85, v8 offset:4992
	ds_read_u16 v86, v8 offset:5120
	ds_read_u16 v87, v8 offset:5248
	ds_read_u16 v88, v8 offset:5376
	ds_read_u16 v89, v8 offset:5504
	ds_read_u16 v90, v8 offset:5632
	ds_read_u16 v91, v8 offset:5760
	ds_read_u16 v92, v8 offset:5888
	s_mov_b32 s50, 0x3e000000
	s_waitcnt lgkmcnt(0)
	v_lshlrev_b32_e32 v54, 16, v54
	v_lshlrev_b32_e32 v55, 16, v55
	v_lshlrev_b32_e32 v56, 16, v56
	v_lshlrev_b32_e32 v57, 16, v57
	v_lshlrev_b32_e32 v58, 16, v58
	v_lshlrev_b32_e32 v59, 16, v59
	v_lshlrev_b32_e32 v60, 16, v60
	v_lshlrev_b32_e32 v61, 16, v61
	v_lshlrev_b32_e32 v62, 16, v62
	v_lshlrev_b32_e32 v63, 16, v63
	v_lshlrev_b32_e32 v64, 16, v64
	v_lshlrev_b32_e32 v65, 16, v65
	v_lshlrev_b32_e32 v66, 16, v66
	v_lshlrev_b32_e32 v67, 16, v67
	v_lshlrev_b32_e32 v68, 16, v68
	v_lshlrev_b32_e32 v69, 16, v69
	v_lshlrev_b32_e32 v70, 16, v70
	v_lshlrev_b32_e32 v71, 16, v71
	v_lshlrev_b32_e32 v72, 16, v72
	v_lshlrev_b32_e32 v73, 16, v73
	v_lshlrev_b32_e32 v74, 16, v74
	v_lshlrev_b32_e32 v75, 16, v75
	v_lshlrev_b32_e32 v76, 16, v76
	v_lshlrev_b32_e32 v77, 16, v77
	v_lshlrev_b32_e32 v78, 16, v78
	v_lshlrev_b32_e32 v79, 16, v79
	v_lshlrev_b32_e32 v80, 16, v80
	v_lshlrev_b32_e32 v81, 16, v81
	v_lshlrev_b32_e32 v82, 16, v82
	v_lshlrev_b32_e32 v83, 16, v83
	v_lshlrev_b32_e32 v84, 16, v84
	v_lshlrev_b32_e32 v85, 16, v85
	v_lshlrev_b32_e32 v86, 16, v86
	v_lshlrev_b32_e32 v87, 16, v87
	v_lshlrev_b32_e32 v88, 16, v88
	v_lshlrev_b32_e32 v89, 16, v89
	v_lshlrev_b32_e32 v90, 16, v90
	v_lshlrev_b32_e32 v91, 16, v91
	v_lshlrev_b32_e32 v92, 16, v92
	s_cmp_eq_u32 s42, 1
	s_cbranch_scc0 .Lpool_nz2
	v_mov_b32_e32 v60, 0
	v_mov_b32_e32 v59, 0
	v_mov_b32_e32 v58, 0
	v_mov_b32_e32 v57, 0
	v_mov_b32_e32 v56, 0
	v_mov_b32_e32 v55, 0
	v_mov_b32_e32 v54, 0
.Lpool_nz2:
	v_add_f32_e32 v93, v61, v60
	v_add_f32_e32 v93, v93, v59
	v_add_f32_e32 v93, v93, v58
	v_add_f32_e32 v93, v93, v57
	v_add_f32_e32 v93, v93, v56
	v_add_f32_e32 v93, v93, v55
	v_add_f32_e32 v93, v93, v54
	s_cmp_eq_u32 s42, 1
	s_cselect_b32 s51, 0x3f800000, s50
	v_fma_f32 v2, v93, s51, -v61
	v_add_f32_e32 v93, v93, v62
	v_sub_f32_e32 v93, v93, v54
	s_cmp_eq_u32 s42, 1
	s_cselect_b32 s51, 0x3f000000, s50
	v_fma_f32 v3, v93, s51, -v62
	v_cvt_pk_bf16_f32 v2, v2, v3
	ds_write_b16 v9, v2 offset:0
	ds_write_b16_d16_hi v9, v2 offset:144
	v_add_f32_e32 v93, v93, v63
	v_sub_f32_e32 v93, v93, v55
	s_cmp_eq_u32 s42, 1
	s_cselect_b32 s51, 0x3eaaaaab, s50
	v_fma_f32 v4, v93, s51, -v63
	v_add_f32_e32 v93, v93, v64
	v_sub_f32_e32 v93, v93, v56
	s_cmp_eq_u32 s42, 1
	s_cselect_b32 s51, 0x3e800000, s50
	v_fma_f32 v5, v93, s51, -v64
	v_cvt_pk_bf16_f32 v4, v4, v5
	ds_write_b16 v9, v4 offset:288
	ds_write_b16_d16_hi v9, v4 offset:432
	v_add_f32_e32 v93, v93, v65
	v_sub_f32_e32 v93, v93, v57
	s_cmp_eq_u32 s42, 1
	s_cselect_b32 s51, 0x3e4ccccd, s50
	v_fma_f32 v2, v93, s51, -v65
	v_add_f32_e32 v93, v93, v66
	v_sub_f32_e32 v93, v93, v58
	s_cmp_eq_u32 s42, 1
	s_cselect_b32 s51, 0x3e2aaaab, s50
	v_fma_f32 v3, v93, s51, -v66
	v_cvt_pk_bf16_f32 v2, v2, v3
	ds_write_b16 v9, v2 offset:576
	ds_write_b16_d16_hi v9, v2 offset:720
	v_add_f32_e32 v93, v93, v67
	v_sub_f32_e32 v93, v93, v59
	s_cmp_eq_u32 s42, 1
	s_cselect_b32 s51, 0x3e124925, s50
	v_fma_f32 v4, v93, s51, -v67
	v_add_f32_e32 v93, v93, v68
	v_sub_f32_e32 v93, v93, v60
	v_fma_f32 v5, v93, s50, -v68
	v_cvt_pk_bf16_f32 v4, v4, v5
	ds_write_b16 v9, v4 offset:864
	ds_write_b16_d16_hi v9, v4 offset:1008
	v_add_f32_e32 v93, v93, v69
	v_sub_f32_e32 v93, v93, v61
	v_fma_f32 v2, v93, s50, -v69
	v_add_f32_e32 v93, v93, v70
	v_sub_f32_e32 v93, v93, v62
	v_fma_f32 v3, v93, s50, -v70
	v_cvt_pk_bf16_f32 v2, v2, v3
	ds_write_b16 v9, v2 offset:1152
	ds_write_b16_d16_hi v9, v2 offset:1296
	v_add_f32_e32 v93, v93, v71
	v_sub_f32_e32 v93, v93, v63
	v_fma_f32 v4, v93, s50, -v71
	v_add_f32_e32 v93, v93, v72
	v_sub_f32_e32 v93, v93, v64
	v_fma_f32 v5, v93, s50, -v72
	v_cvt_pk_bf16_f32 v4, v4, v5
	ds_write_b16 v9, v4 offset:1440
	ds_write_b16_d16_hi v9, v4 offset:1584
	v_add_f32_e32 v93, v93, v73
	v_sub_f32_e32 v93, v93, v65
	v_fma_f32 v2, v93, s50, -v73
	v_add_f32_e32 v93, v93, v74
	v_sub_f32_e32 v93, v93, v66
	v_fma_f32 v3, v93, s50, -v74
	v_cvt_pk_bf16_f32 v2, v2, v3
	ds_write_b16 v9, v2 offset:1728
	ds_write_b16_d16_hi v9, v2 offset:1872
	v_add_f32_e32 v93, v93, v75
	v_sub_f32_e32 v93, v93, v67
	v_fma_f32 v4, v93, s50, -v75
	v_add_f32_e32 v93, v93, v76
	v_sub_f32_e32 v93, v93, v68
	v_fma_f32 v5, v93, s50, -v76
	v_cvt_pk_bf16_f32 v4, v4, v5
	ds_write_b16 v9, v4 offset:2016
	ds_write_b16_d16_hi v9, v4 offset:2160
	v_add_f32_e32 v93, v93, v77
	v_sub_f32_e32 v93, v93, v69
	v_fma_f32 v2, v93, s50, -v77
	v_add_f32_e32 v93, v93, v78
	v_sub_f32_e32 v93, v93, v70
	v_fma_f32 v3, v93, s50, -v78
	v_cvt_pk_bf16_f32 v2, v2, v3
	ds_write_b16 v9, v2 offset:2304
	ds_write_b16_d16_hi v9, v2 offset:2448
	v_add_f32_e32 v93, v93, v79
	v_sub_f32_e32 v93, v93, v71
	v_fma_f32 v4, v93, s50, -v79
	v_add_f32_e32 v93, v93, v80
	v_sub_f32_e32 v93, v93, v72
	v_fma_f32 v5, v93, s50, -v80
	v_cvt_pk_bf16_f32 v4, v4, v5
	ds_write_b16 v9, v4 offset:2592
	ds_write_b16_d16_hi v9, v4 offset:2736
	v_add_f32_e32 v93, v93, v81
	v_sub_f32_e32 v93, v93, v73
	v_fma_f32 v2, v93, s50, -v81
	v_add_f32_e32 v93, v93, v82
	v_sub_f32_e32 v93, v93, v74
	v_fma_f32 v3, v93, s50, -v82
	v_cvt_pk_bf16_f32 v2, v2, v3
	ds_write_b16 v9, v2 offset:2880
	ds_write_b16_d16_hi v9, v2 offset:3024
	v_add_f32_e32 v93, v93, v83
	v_sub_f32_e32 v93, v93, v75
	v_fma_f32 v4, v93, s50, -v83
	v_add_f32_e32 v93, v93, v84
	v_sub_f32_e32 v93, v93, v76
	v_fma_f32 v5, v93, s50, -v84
	v_cvt_pk_bf16_f32 v4, v4, v5
	ds_write_b16 v9, v4 offset:3168
	ds_write_b16_d16_hi v9, v4 offset:3312
	v_add_f32_e32 v93, v93, v85
	v_sub_f32_e32 v93, v93, v77
	v_fma_f32 v2, v93, s50, -v85
	v_add_f32_e32 v93, v93, v86
	v_sub_f32_e32 v93, v93, v78
	v_fma_f32 v3, v93, s50, -v86
	v_cvt_pk_bf16_f32 v2, v2, v3
	ds_write_b16 v9, v2 offset:3456
	ds_write_b16_d16_hi v9, v2 offset:3600
	v_add_f32_e32 v93, v93, v87
	v_sub_f32_e32 v93, v93, v79
	v_fma_f32 v4, v93, s50, -v87
	v_add_f32_e32 v93, v93, v88
	v_sub_f32_e32 v93, v93, v80
	v_fma_f32 v5, v93, s50, -v88
	v_cvt_pk_bf16_f32 v4, v4, v5
	ds_write_b16 v9, v4 offset:3744
	ds_write_b16_d16_hi v9, v4 offset:3888
	v_add_f32_e32 v93, v93, v89
	v_sub_f32_e32 v93, v93, v81
	v_fma_f32 v2, v93, s50, -v89
	v_add_f32_e32 v93, v93, v90
	v_sub_f32_e32 v93, v93, v82
	v_fma_f32 v3, v93, s50, -v90
	v_cvt_pk_bf16_f32 v2, v2, v3
	ds_write_b16 v9, v2 offset:4032
	ds_write_b16_d16_hi v9, v2 offset:4176
	v_add_f32_e32 v93, v93, v91
	v_sub_f32_e32 v93, v93, v83
	v_fma_f32 v4, v93, s50, -v91
	v_add_f32_e32 v93, v93, v92
	v_sub_f32_e32 v93, v93, v84
	v_fma_f32 v5, v93, s50, -v92
	v_cvt_pk_bf16_f32 v4, v4, v5
	ds_write_b16 v9, v4 offset:4320
	ds_write_b16_d16_hi v9, v4 offset:4464
	v_and_b32_e32 v2, 31, v0
	v_lshrrev_b32_e32 v3, 5, v0
	v_bfe_u32 v4, v0, 1, 3
	v_xor_b32_e32 v3, v3, v4
	v_lshlrev_b32_e32 v2, 7, v2
	v_add_u32_e32 v2, 0x1a000, v2
	v_lshl_add_u32 v5, v3, 4, v2
	v_xor_b32_e32 v4, 2, v3
	v_lshl_add_u32 v4, v4, 4, v2
	v_xor_b32_e32 v88, 4, v3
	v_xor_b32_e32 v3, 6, v3
	v_lshl_add_u32 v3, v3, 4, v2
	v_lshl_add_u32 v2, v88, 4, v2
	s_waitcnt lgkmcnt(0)
	ds_read_b128 v[28:31], v5 offset:0
	ds_read_b128 v[32:35], v5 offset:4096
	ds_read_b128 v[78:81], v44 offset:0
	ds_read_b128 v[82:85], v44 offset:32
	ds_read_b128 v[86:89], v44 offset:64
	ds_read_b128 v[90:93], v44 offset:96
	ds_read_b128 v[36:39], v4 offset:0
	ds_read_b128 v[40:43], v4 offset:4096
	s_waitcnt lgkmcnt(0)
	v_mfma_f32_32x32x16_bf16 v[46:61], v[28:31], v[78:81], 0
	v_mfma_f32_32x32x16_bf16 v[62:77], v[32:35], v[78:81], 0
	ds_read_b128 v[28:31], v2 offset:0
	ds_read_b128 v[32:35], v2 offset:4096
	v_mfma_f32_32x32x16_bf16 v[46:61], v[36:39], v[82:85], v[46:61]
	v_mfma_f32_32x32x16_bf16 v[62:77], v[40:43], v[82:85], v[62:77]
	ds_read_b128 v[36:39], v3 offset:0
	ds_read_b128 v[40:43], v3 offset:4096
	s_waitcnt lgkmcnt(2)
	v_mfma_f32_32x32x16_bf16 v[46:61], v[28:31], v[86:89], v[46:61]
	v_mfma_f32_32x32x16_bf16 v[62:77], v[32:35], v[86:89], v[62:77]
	s_waitcnt lgkmcnt(0)
	v_mfma_f32_32x32x16_bf16 v[46:61], v[36:39], v[90:93], v[46:61]
	v_mfma_f32_32x32x16_bf16 v[62:77], v[40:43], v[90:93], v[62:77]
	v_lshl_add_u64 v[4:5], s[52:53], 0, v[10:11]
	s_nop 14
	s_waitcnt vmcnt(5)
	s_mov_b32 s56, 0xbfb8aa3b
	s_mov_b32 s57, 0xbfb8aa3b
	s_mov_b32 s54, 1.0
	s_mov_b32 s55, 1.0
	v_lshlrev_b32_e32 v78, 16, v12
	v_and_b32_e32 v79, 0xffff0000, v12
	v_lshlrev_b32_e32 v80, 16, v13
	v_and_b32_e32 v81, 0xffff0000, v13
	v_lshlrev_b32_e32 v82, 16, v14
	v_and_b32_e32 v83, 0xffff0000, v14
	v_lshlrev_b32_e32 v84, 16, v15
	v_and_b32_e32 v85, 0xffff0000, v15
	v_lshlrev_b32_e32 v86, 16, v16
	v_and_b32_e32 v87, 0xffff0000, v16
	v_lshlrev_b32_e32 v88, 16, v17
	v_and_b32_e32 v89, 0xffff0000, v17
	v_lshlrev_b32_e32 v90, 16, v18
	v_and_b32_e32 v91, 0xffff0000, v18
	v_lshlrev_b32_e32 v92, 16, v19
	v_and_b32_e32 v93, 0xffff0000, v19
	v_pk_mul_f32 v[28:29], v[78:79], s[56:57]
	v_pk_mul_f32 v[30:31], v[80:81], s[56:57]
	v_pk_mul_f32 v[32:33], v[82:83], s[56:57]
	v_pk_mul_f32 v[34:35], v[84:85], s[56:57]
	v_pk_mul_f32 v[36:37], v[86:87], s[56:57]
	v_pk_mul_f32 v[38:39], v[88:89], s[56:57]
	v_pk_mul_f32 v[40:41], v[90:91], s[56:57]
	v_pk_mul_f32 v[42:43], v[92:93], s[56:57]
	v_exp_f32_e32 v28, v28
	v_exp_f32_e32 v29, v29
	v_exp_f32_e32 v30, v30
	v_exp_f32_e32 v31, v31
	v_exp_f32_e32 v32, v32
	v_exp_f32_e32 v33, v33
	v_exp_f32_e32 v34, v34
	v_exp_f32_e32 v35, v35
	v_exp_f32_e32 v36, v36
	v_exp_f32_e32 v37, v37
	v_exp_f32_e32 v38, v38
	v_exp_f32_e32 v39, v39
	v_exp_f32_e32 v40, v40
	v_exp_f32_e32 v41, v41
	v_exp_f32_e32 v42, v42
	v_exp_f32_e32 v43, v43
	v_pk_add_f32 v[28:29], v[28:29], s[54:55]
	v_pk_add_f32 v[30:31], v[30:31], s[54:55]
	v_pk_add_f32 v[32:33], v[32:33], s[54:55]
	v_pk_add_f32 v[34:35], v[34:35], s[54:55]
	v_pk_add_f32 v[36:37], v[36:37], s[54:55]
	v_pk_add_f32 v[38:39], v[38:39], s[54:55]
	v_pk_add_f32 v[40:41], v[40:41], s[54:55]
	v_pk_add_f32 v[42:43], v[42:43], s[54:55]
	v_rcp_f32_e32 v28, v28
	v_rcp_f32_e32 v29, v29
	v_rcp_f32_e32 v30, v30
	v_rcp_f32_e32 v31, v31
	v_rcp_f32_e32 v32, v32
	v_rcp_f32_e32 v33, v33
	v_rcp_f32_e32 v34, v34
	v_rcp_f32_e32 v35, v35
	v_rcp_f32_e32 v36, v36
	v_rcp_f32_e32 v37, v37
	v_rcp_f32_e32 v38, v38
	v_rcp_f32_e32 v39, v39
	v_rcp_f32_e32 v40, v40
	v_rcp_f32_e32 v41, v41
	v_rcp_f32_e32 v42, v42
	v_rcp_f32_e32 v43, v43
	v_pk_mul_f32 v[28:29], v[78:79], v[28:29]
	v_pk_mul_f32 v[30:31], v[80:81], v[30:31]
	v_pk_mul_f32 v[32:33], v[82:83], v[32:33]
	v_pk_mul_f32 v[34:35], v[84:85], v[34:35]
	v_pk_mul_f32 v[36:37], v[86:87], v[36:37]
	v_pk_mul_f32 v[38:39], v[88:89], v[38:39]
	v_pk_mul_f32 v[40:41], v[90:91], v[40:41]
	v_pk_mul_f32 v[42:43], v[92:93], v[42:43]
	v_pk_mul_f32 v[28:29], v[46:47], v[28:29]
	v_pk_mul_f32 v[30:31], v[48:49], v[30:31]
	v_pk_mul_f32 v[32:33], v[50:51], v[32:33]
	v_pk_mul_f32 v[34:35], v[52:53], v[34:35]
	v_pk_mul_f32 v[36:37], v[54:55], v[36:37]
	v_pk_mul_f32 v[38:39], v[56:57], v[38:39]
	v_pk_mul_f32 v[40:41], v[58:59], v[40:41]
	v_pk_mul_f32 v[42:43], v[60:61], v[42:43]
	v_cvt_pk_bf16_f32 v78, v28, v29
	v_cvt_pk_bf16_f32 v79, v30, v31
	v_cvt_pk_bf16_f32 v80, v32, v33
	v_cvt_pk_bf16_f32 v81, v34, v35
	v_cvt_pk_bf16_f32 v82, v36, v37
	v_cvt_pk_bf16_f32 v83, v38, v39
	v_cvt_pk_bf16_f32 v84, v40, v41
	v_cvt_pk_bf16_f32 v85, v42, v43
	global_store_dwordx2 v[4:5], v[78:79], off offset:256
	global_store_dwordx2 v[4:5], v[80:81], off offset:272
	global_store_dwordx2 v[4:5], v[82:83], off offset:288
	global_store_dwordx2 v[4:5], v[84:85], off offset:304
	v_lshlrev_b32_e32 v78, 16, v20
	v_and_b32_e32 v79, 0xffff0000, v20
	v_lshlrev_b32_e32 v80, 16, v21
	v_and_b32_e32 v81, 0xffff0000, v21
	v_lshlrev_b32_e32 v82, 16, v22
	v_and_b32_e32 v83, 0xffff0000, v22
	v_lshlrev_b32_e32 v84, 16, v23
	v_and_b32_e32 v85, 0xffff0000, v23
	v_lshlrev_b32_e32 v86, 16, v24
	v_and_b32_e32 v87, 0xffff0000, v24
	v_lshlrev_b32_e32 v88, 16, v25
	v_and_b32_e32 v89, 0xffff0000, v25
	v_lshlrev_b32_e32 v90, 16, v26
	v_and_b32_e32 v91, 0xffff0000, v26
	v_lshlrev_b32_e32 v92, 16, v27
	v_and_b32_e32 v93, 0xffff0000, v27
	v_pk_mul_f32 v[28:29], v[78:79], s[56:57]
	v_pk_mul_f32 v[30:31], v[80:81], s[56:57]
	v_pk_mul_f32 v[32:33], v[82:83], s[56:57]
	v_pk_mul_f32 v[34:35], v[84:85], s[56:57]
	v_pk_mul_f32 v[36:37], v[86:87], s[56:57]
	v_pk_mul_f32 v[38:39], v[88:89], s[56:57]
	v_pk_mul_f32 v[40:41], v[90:91], s[56:57]
	v_pk_mul_f32 v[42:43], v[92:93], s[56:57]
	v_exp_f32_e32 v28, v28
	v_exp_f32_e32 v29, v29
	v_exp_f32_e32 v30, v30
	v_exp_f32_e32 v31, v31
	v_exp_f32_e32 v32, v32
	v_exp_f32_e32 v33, v33
	v_exp_f32_e32 v34, v34
	v_exp_f32_e32 v35, v35
	v_exp_f32_e32 v36, v36
	v_exp_f32_e32 v37, v37
	v_exp_f32_e32 v38, v38
	v_exp_f32_e32 v39, v39
	v_exp_f32_e32 v40, v40
	v_exp_f32_e32 v41, v41
	v_exp_f32_e32 v42, v42
	v_exp_f32_e32 v43, v43
	v_pk_add_f32 v[28:29], v[28:29], s[54:55]
	v_pk_add_f32 v[30:31], v[30:31], s[54:55]
	v_pk_add_f32 v[32:33], v[32:33], s[54:55]
	v_pk_add_f32 v[34:35], v[34:35], s[54:55]
	v_pk_add_f32 v[36:37], v[36:37], s[54:55]
	v_pk_add_f32 v[38:39], v[38:39], s[54:55]
	v_pk_add_f32 v[40:41], v[40:41], s[54:55]
	v_pk_add_f32 v[42:43], v[42:43], s[54:55]
	v_rcp_f32_e32 v28, v28
	v_rcp_f32_e32 v29, v29
	v_rcp_f32_e32 v30, v30
	v_rcp_f32_e32 v31, v31
	v_rcp_f32_e32 v32, v32
	v_rcp_f32_e32 v33, v33
	v_rcp_f32_e32 v34, v34
	v_rcp_f32_e32 v35, v35
	v_rcp_f32_e32 v36, v36
	v_rcp_f32_e32 v37, v37
	v_rcp_f32_e32 v38, v38
	v_rcp_f32_e32 v39, v39
	v_rcp_f32_e32 v40, v40
	v_rcp_f32_e32 v41, v41
	v_rcp_f32_e32 v42, v42
	v_rcp_f32_e32 v43, v43
	v_pk_mul_f32 v[28:29], v[78:79], v[28:29]
	v_pk_mul_f32 v[30:31], v[80:81], v[30:31]
	v_pk_mul_f32 v[32:33], v[82:83], v[32:33]
	v_pk_mul_f32 v[34:35], v[84:85], v[34:35]
	v_pk_mul_f32 v[36:37], v[86:87], v[36:37]
	v_pk_mul_f32 v[38:39], v[88:89], v[38:39]
	v_pk_mul_f32 v[40:41], v[90:91], v[40:41]
	v_pk_mul_f32 v[42:43], v[92:93], v[42:43]
	v_pk_mul_f32 v[28:29], v[62:63], v[28:29]
	v_pk_mul_f32 v[30:31], v[64:65], v[30:31]
	v_pk_mul_f32 v[32:33], v[66:67], v[32:33]
	v_pk_mul_f32 v[34:35], v[68:69], v[34:35]
	v_pk_mul_f32 v[36:37], v[70:71], v[36:37]
	v_pk_mul_f32 v[38:39], v[72:73], v[38:39]
	v_pk_mul_f32 v[40:41], v[74:75], v[40:41]
	v_pk_mul_f32 v[42:43], v[76:77], v[42:43]
	v_cvt_pk_bf16_f32 v78, v28, v29
	v_cvt_pk_bf16_f32 v79, v30, v31
	v_cvt_pk_bf16_f32 v80, v32, v33
	v_cvt_pk_bf16_f32 v81, v34, v35
	v_cvt_pk_bf16_f32 v82, v36, v37
	v_cvt_pk_bf16_f32 v83, v38, v39
	v_cvt_pk_bf16_f32 v84, v40, v41
	v_cvt_pk_bf16_f32 v85, v42, v43
	global_store_dwordx2 v[4:5], v[78:79], off offset:320
	global_store_dwordx2 v[4:5], v[80:81], off offset:336
	global_store_dwordx2 v[4:5], v[82:83], off offset:352
	global_store_dwordx2 v[4:5], v[84:85], off offset:368
	v_lshl_add_u64 v[4:5], s[52:53], 0, v[10:11]
	global_load_dwordx2 v[12:13], v[4:5], off offset:384
	global_load_dwordx2 v[14:15], v[4:5], off offset:400
	global_load_dwordx2 v[16:17], v[4:5], off offset:416
	global_load_dwordx2 v[18:19], v[4:5], off offset:432
	global_load_dwordx2 v[20:21], v[4:5], off offset:448
	global_load_dwordx2 v[22:23], v[4:5], off offset:464
	global_load_dwordx2 v[24:25], v[4:5], off offset:480
	global_load_dwordx2 v[26:27], v[4:5], off offset:496
	s_waitcnt vmcnt(8)
	s_barrier
	ds_read_u16 v46, v8 offset:34816
	ds_read_u16 v47, v8 offset:34944
	ds_read_u16 v48, v8 offset:35072
	ds_read_u16 v49, v8 offset:35200
	ds_read_u16 v50, v8 offset:35328
	ds_read_u16 v51, v8 offset:35456
	ds_read_u16 v52, v8 offset:35584
	ds_read_u16 v53, v8 offset:35712
	ds_read_u16 v54, v8 offset:35840
	ds_read_u16 v55, v8 offset:35968
	ds_read_u16 v56, v8 offset:36096
	ds_read_u16 v57, v8 offset:36224
	ds_read_u16 v58, v8 offset:36352
	ds_read_u16 v59, v8 offset:36480
	ds_read_u16 v60, v8 offset:36608
	ds_read_u16 v61, v8 offset:36736
	ds_read_u16 v62, v8 offset:36864
	ds_read_u16 v63, v8 offset:36992
	ds_read_u16 v64, v8 offset:37120
	ds_read_u16 v65, v8 offset:37248
	ds_read_u16 v66, v8 offset:37376
	ds_read_u16 v67, v8 offset:37504
	ds_read_u16 v68, v8 offset:37632
	ds_read_u16 v69, v8 offset:37760
	ds_read_u16 v70, v8 offset:37888
	ds_read_u16 v71, v8 offset:38016
	ds_read_u16 v72, v8 offset:38144
	ds_read_u16 v73, v8 offset:38272
	ds_read_u16 v74, v8 offset:38400
	ds_read_u16 v75, v8 offset:38528
	ds_read_u16 v76, v8 offset:38656
	ds_read_u16 v77, v8 offset:38784
	ds_read_u16 v78, v8 offset:38912
	ds_read_u16 v79, v8 offset:39040
	ds_read_u16 v80, v8 offset:39168
	ds_read_u16 v81, v8 offset:39296
	ds_read_u16 v82, v8 offset:39424
	ds_read_u16 v83, v8 offset:39552
	ds_read_u16 v84, v8 offset:39680
	ds_read_u16 v85, v8 offset:39808
	ds_read_u16 v86, v8 offset:39936
	ds_read_u16 v87, v8 offset:40064
	ds_read_u16 v88, v8 offset:40192
	ds_read_u16 v89, v8 offset:40320
	ds_read_u16 v90, v8 offset:40448
	ds_read_u16 v91, v8 offset:40576
	ds_read_u16 v92, v8 offset:40704
	s_mov_b32 s50, 0x3d800000
	s_waitcnt lgkmcnt(0)
	v_lshlrev_b32_e32 v46, 16, v46
	v_lshlrev_b32_e32 v47, 16, v47
	v_lshlrev_b32_e32 v48, 16, v48
	v_lshlrev_b32_e32 v49, 16, v49
	v_lshlrev_b32_e32 v50, 16, v50
	v_lshlrev_b32_e32 v51, 16, v51
	v_lshlrev_b32_e32 v52, 16, v52
	v_lshlrev_b32_e32 v53, 16, v53
	v_lshlrev_b32_e32 v54, 16, v54
	v_lshlrev_b32_e32 v55, 16, v55
	v_lshlrev_b32_e32 v56, 16, v56
	v_lshlrev_b32_e32 v57, 16, v57
	v_lshlrev_b32_e32 v58, 16, v58
	v_lshlrev_b32_e32 v59, 16, v59
	v_lshlrev_b32_e32 v60, 16, v60
	v_lshlrev_b32_e32 v61, 16, v61
	v_lshlrev_b32_e32 v62, 16, v62
	v_lshlrev_b32_e32 v63, 16, v63
	v_lshlrev_b32_e32 v64, 16, v64
	v_lshlrev_b32_e32 v65, 16, v65
	v_lshlrev_b32_e32 v66, 16, v66
	v_lshlrev_b32_e32 v67, 16, v67
	v_lshlrev_b32_e32 v68, 16, v68
	v_lshlrev_b32_e32 v69, 16, v69
	v_lshlrev_b32_e32 v70, 16, v70
	v_lshlrev_b32_e32 v71, 16, v71
	v_lshlrev_b32_e32 v72, 16, v72
	v_lshlrev_b32_e32 v73, 16, v73
	v_lshlrev_b32_e32 v74, 16, v74
	v_lshlrev_b32_e32 v75, 16, v75
	v_lshlrev_b32_e32 v76, 16, v76
	v_lshlrev_b32_e32 v77, 16, v77
	v_lshlrev_b32_e32 v78, 16, v78
	v_lshlrev_b32_e32 v79, 16, v79
	v_lshlrev_b32_e32 v80, 16, v80
	v_lshlrev_b32_e32 v81, 16, v81
	v_lshlrev_b32_e32 v82, 16, v82
	v_lshlrev_b32_e32 v83, 16, v83
	v_lshlrev_b32_e32 v84, 16, v84
	v_lshlrev_b32_e32 v85, 16, v85
	v_lshlrev_b32_e32 v86, 16, v86
	v_lshlrev_b32_e32 v87, 16, v87
	v_lshlrev_b32_e32 v88, 16, v88
	v_lshlrev_b32_e32 v89, 16, v89
	v_lshlrev_b32_e32 v90, 16, v90
	v_lshlrev_b32_e32 v91, 16, v91
	v_lshlrev_b32_e32 v92, 16, v92
	s_cmp_eq_u32 s42, 1
	s_cbranch_scc0 .Lpool_nz3
	v_mov_b32_e32 v60, 0
	v_mov_b32_e32 v59, 0
	v_mov_b32_e32 v58, 0
	v_mov_b32_e32 v57, 0
	v_mov_b32_e32 v56, 0
	v_mov_b32_e32 v55, 0
	v_mov_b32_e32 v54, 0
	v_mov_b32_e32 v53, 0
	v_mov_b32_e32 v52, 0
	v_mov_b32_e32 v51, 0
	v_mov_b32_e32 v50, 0
	v_mov_b32_e32 v49, 0
	v_mov_b32_e32 v48, 0
	v_mov_b32_e32 v47, 0
	v_mov_b32_e32 v46, 0
.Lpool_nz3:
	v_add_f32_e32 v93, v61, v60
	v_add_f32_e32 v93, v93, v59
	v_add_f32_e32 v93, v93, v58
	v_add_f32_e32 v93, v93, v57
	v_add_f32_e32 v93, v93, v56
	v_add_f32_e32 v93, v93, v55
	v_add_f32_e32 v93, v93, v54
	v_add_f32_e32 v93, v93, v53
	v_add_f32_e32 v93, v93, v52
	v_add_f32_e32 v93, v93, v51
	v_add_f32_e32 v93, v93, v50
	v_add_f32_e32 v93, v93, v49
	v_add_f32_e32 v93, v93, v48
	v_add_f32_e32 v93, v93, v47
	v_add_f32_e32 v93, v93, v46
	s_cmp_eq_u32 s42, 1
	s_cselect_b32 s51, 0x3f800000, s50
	v_fma_f32 v2, v93, s51, -v61
	v_add_f32_e32 v93, v93, v62
	v_sub_f32_e32 v93, v93, v46
	s_cmp_eq_u32 s42, 1
	s_cselect_b32 s51, 0x3f000000, s50
	v_fma_f32 v3, v93, s51, -v62
	v_cvt_pk_bf16_f32 v2, v2, v3
	ds_write_b16 v9, v2 offset:0
	ds_write_b16_d16_hi v9, v2 offset:144
	v_add_f32_e32 v93, v93, v63
	v_sub_f32_e32 v93, v93, v47
	s_cmp_eq_u32 s42, 1
	s_cselect_b32 s51, 0x3eaaaaab, s50
	v_fma_f32 v4, v93, s51, -v63
	v_add_f32_e32 v93, v93, v64
	v_sub_f32_e32 v93, v93, v48
	s_cmp_eq_u32 s42, 1
	s_cselect_b32 s51, 0x3e800000, s50
	v_fma_f32 v5, v93, s51, -v64
	v_cvt_pk_bf16_f32 v4, v4, v5
	ds_write_b16 v9, v4 offset:288
	ds_write_b16_d16_hi v9, v4 offset:432
	v_add_f32_e32 v93, v93, v65
	v_sub_f32_e32 v93, v93, v49
	s_cmp_eq_u32 s42, 1
	s_cselect_b32 s51, 0x3e4ccccd, s50
	v_fma_f32 v2, v93, s51, -v65
	v_add_f32_e32 v93, v93, v66
	v_sub_f32_e32 v93, v93, v50
	s_cmp_eq_u32 s42, 1
	s_cselect_b32 s51, 0x3e2aaaab, s50
	v_fma_f32 v3, v93, s51, -v66
	v_cvt_pk_bf16_f32 v2, v2, v3
	ds_write_b16 v9, v2 offset:576
	ds_write_b16_d16_hi v9, v2 offset:720
	v_add_f32_e32 v93, v93, v67
	v_sub_f32_e32 v93, v93, v51
	s_cmp_eq_u32 s42, 1
	s_cselect_b32 s51, 0x3e124925, s50
	v_fma_f32 v4, v93, s51, -v67
	v_add_f32_e32 v93, v93, v68
	v_sub_f32_e32 v93, v93, v52
	s_cmp_eq_u32 s42, 1
	s_cselect_b32 s51, 0x3e000000, s50
	v_fma_f32 v5, v93, s51, -v68
	v_cvt_pk_bf16_f32 v4, v4, v5
	ds_write_b16 v9, v4 offset:864
	ds_write_b16_d16_hi v9, v4 offset:1008
	v_add_f32_e32 v93, v93, v69
	v_sub_f32_e32 v93, v93, v53
	s_cmp_eq_u32 s42, 1
	s_cselect_b32 s51, 0x3de38e39, s50
	v_fma_f32 v2, v93, s51, -v69
	v_add_f32_e32 v93, v93, v70
	v_sub_f32_e32 v93, v93, v54
	s_cmp_eq_u32 s42, 1
	s_cselect_b32 s51, 0x3dcccccd, s50
	v_fma_f32 v3, v93, s51, -v70
	v_cvt_pk_bf16_f32 v2, v2, v3
	ds_write_b16 v9, v2 offset:1152
	ds_write_b16_d16_hi v9, v2 offset:1296
	v_add_f32_e32 v93, v93, v71
	v_sub_f32_e32 v93, v93, v55
	s_cmp_eq_u32 s42, 1
	s_cselect_b32 s51, 0x3dba2e8c, s50
	v_fma_f32 v4, v93, s51, -v71
	v_add_f32_e32 v93, v93, v72
	v_sub_f32_e32 v93, v93, v56
	s_cmp_eq_u32 s42, 1
	s_cselect_b32 s51, 0x3daaaaab, s50
	v_fma_f32 v5, v93, s51, -v72
	v_cvt_pk_bf16_f32 v4, v4, v5
	ds_write_b16 v9, v4 offset:1440
	ds_write_b16_d16_hi v9, v4 offset:1584
	v_add_f32_e32 v93, v93, v73
	v_sub_f32_e32 v93, v93, v57
	s_cmp_eq_u32 s42, 1
	s_cselect_b32 s51, 0x3d9d89d9, s50
	v_fma_f32 v2, v93, s51, -v73
	v_add_f32_e32 v93, v93, v74
	v_sub_f32_e32 v93, v93, v58
	s_cmp_eq_u32 s42, 1
	s_cselect_b32 s51, 0x3d924925, s50
	v_fma_f32 v3, v93, s51, -v74
	v_cvt_pk_bf16_f32 v2, v2, v3
	ds_write_b16 v9, v2 offset:1728
	ds_write_b16_d16_hi v9, v2 offset:1872
	v_add_f32_e32 v93, v93, v75
	v_sub_f32_e32 v93, v93, v59
	s_cmp_eq_u32 s42, 1
	s_cselect_b32 s51, 0x3d888889, s50
	v_fma_f32 v4, v93, s51, -v75
	v_add_f32_e32 v93, v93, v76
	v_sub_f32_e32 v93, v93, v60
	v_fma_f32 v5, v93, s50, -v76
	v_cvt_pk_bf16_f32 v4, v4, v5
	ds_write_b16 v9, v4 offset:2016
	ds_write_b16_d16_hi v9, v4 offset:2160
	v_add_f32_e32 v93, v93, v77
	v_sub_f32_e32 v93, v93, v61
	v_fma_f32 v2, v93, s50, -v77
	v_add_f32_e32 v93, v93, v78
	v_sub_f32_e32 v93, v93, v62
	v_fma_f32 v3, v93, s50, -v78
	v_cvt_pk_bf16_f32 v2, v2, v3
	ds_write_b16 v9, v2 offset:2304
	ds_write_b16_d16_hi v9, v2 offset:2448
	v_add_f32_e32 v93, v93, v79
	v_sub_f32_e32 v93, v93, v63
	v_fma_f32 v4, v93, s50, -v79
	v_add_f32_e32 v93, v93, v80
	v_sub_f32_e32 v93, v93, v64
	v_fma_f32 v5, v93, s50, -v80
	v_cvt_pk_bf16_f32 v4, v4, v5
	ds_write_b16 v9, v4 offset:2592
	ds_write_b16_d16_hi v9, v4 offset:2736
	v_add_f32_e32 v93, v93, v81
	v_sub_f32_e32 v93, v93, v65
	v_fma_f32 v2, v93, s50, -v81
	v_add_f32_e32 v93, v93, v82
	v_sub_f32_e32 v93, v93, v66
	v_fma_f32 v3, v93, s50, -v82
	v_cvt_pk_bf16_f32 v2, v2, v3
	ds_write_b16 v9, v2 offset:2880
	ds_write_b16_d16_hi v9, v2 offset:3024
	v_add_f32_e32 v93, v93, v83
	v_sub_f32_e32 v93, v93, v67
	v_fma_f32 v4, v93, s50, -v83
	v_add_f32_e32 v93, v93, v84
	v_sub_f32_e32 v93, v93, v68
	v_fma_f32 v5, v93, s50, -v84
	v_cvt_pk_bf16_f32 v4, v4, v5
	ds_write_b16 v9, v4 offset:3168
	ds_write_b16_d16_hi v9, v4 offset:3312
	v_add_f32_e32 v93, v93, v85
	v_sub_f32_e32 v93, v93, v69
	v_fma_f32 v2, v93, s50, -v85
	v_add_f32_e32 v93, v93, v86
	v_sub_f32_e32 v93, v93, v70
	v_fma_f32 v3, v93, s50, -v86
	v_cvt_pk_bf16_f32 v2, v2, v3
	ds_write_b16 v9, v2 offset:3456
	ds_write_b16_d16_hi v9, v2 offset:3600
	v_add_f32_e32 v93, v93, v87
	v_sub_f32_e32 v93, v93, v71
	v_fma_f32 v4, v93, s50, -v87
	v_add_f32_e32 v93, v93, v88
	v_sub_f32_e32 v93, v93, v72
	v_fma_f32 v5, v93, s50, -v88
	v_cvt_pk_bf16_f32 v4, v4, v5
	ds_write_b16 v9, v4 offset:3744
	ds_write_b16_d16_hi v9, v4 offset:3888
	v_add_f32_e32 v93, v93, v89
	v_sub_f32_e32 v93, v93, v73
	v_fma_f32 v2, v93, s50, -v89
	v_add_f32_e32 v93, v93, v90
	v_sub_f32_e32 v93, v93, v74
	v_fma_f32 v3, v93, s50, -v90
	v_cvt_pk_bf16_f32 v2, v2, v3
	ds_write_b16 v9, v2 offset:4032
	ds_write_b16_d16_hi v9, v2 offset:4176
	v_add_f32_e32 v93, v93, v91
	v_sub_f32_e32 v93, v93, v75
	v_fma_f32 v4, v93, s50, -v91
	v_add_f32_e32 v93, v93, v92
	v_sub_f32_e32 v93, v93, v76
	v_fma_f32 v5, v93, s50, -v92
	v_cvt_pk_bf16_f32 v4, v4, v5
	ds_write_b16 v9, v4 offset:4320
	ds_write_b16_d16_hi v9, v4 offset:4464
	v_and_b32_e32 v2, 31, v0
	v_lshrrev_b32_e32 v3, 5, v0
	v_bfe_u32 v4, v0, 1, 3
	v_xor_b32_e32 v3, v3, v4
	v_lshlrev_b32_e32 v2, 7, v2
	v_add_u32_e32 v2, 0x1c000, v2
	v_lshl_add_u32 v5, v3, 4, v2
	v_xor_b32_e32 v4, 2, v3
	v_lshl_add_u32 v4, v4, 4, v2
	v_xor_b32_e32 v88, 4, v3
	v_xor_b32_e32 v3, 6, v3
	v_lshl_add_u32 v3, v3, 4, v2
	v_lshl_add_u32 v2, v88, 4, v2
	s_waitcnt lgkmcnt(0)
	ds_read_b128 v[28:31], v5 offset:0
	ds_read_b128 v[32:35], v5 offset:4096
	ds_read_b128 v[78:81], v44 offset:0
	ds_read_b128 v[82:85], v44 offset:32
	ds_read_b128 v[86:89], v44 offset:64
	ds_read_b128 v[90:93], v44 offset:96
	ds_read_b128 v[36:39], v4 offset:0
	ds_read_b128 v[40:43], v4 offset:4096
	s_waitcnt lgkmcnt(0)
	v_mfma_f32_32x32x16_bf16 v[46:61], v[28:31], v[78:81], 0
	v_mfma_f32_32x32x16_bf16 v[62:77], v[32:35], v[78:81], 0
	ds_read_b128 v[28:31], v2 offset:0
	ds_read_b128 v[32:35], v2 offset:4096
	v_mfma_f32_32x32x16_bf16 v[46:61], v[36:39], v[82:85], v[46:61]
	v_mfma_f32_32x32x16_bf16 v[62:77], v[40:43], v[82:85], v[62:77]
	ds_read_b128 v[36:39], v3 offset:0
	ds_read_b128 v[40:43], v3 offset:4096
	s_waitcnt lgkmcnt(2)
	v_mfma_f32_32x32x16_bf16 v[46:61], v[28:31], v[86:89], v[46:61]
	v_mfma_f32_32x32x16_bf16 v[62:77], v[32:35], v[86:89], v[62:77]
	s_waitcnt lgkmcnt(0)
	v_mfma_f32_32x32x16_bf16 v[46:61], v[36:39], v[90:93], v[46:61]
	v_mfma_f32_32x32x16_bf16 v[62:77], v[40:43], v[90:93], v[62:77]
	v_lshl_add_u64 v[4:5], s[52:53], 0, v[10:11]
	s_nop 14
	s_waitcnt vmcnt(0)
	s_mov_b32 s56, 0xbfb8aa3b
	s_mov_b32 s57, 0xbfb8aa3b
	s_mov_b32 s54, 1.0
	s_mov_b32 s55, 1.0
	v_lshlrev_b32_e32 v78, 16, v12
	v_and_b32_e32 v79, 0xffff0000, v12
	v_lshlrev_b32_e32 v80, 16, v13
	v_and_b32_e32 v81, 0xffff0000, v13
	v_lshlrev_b32_e32 v82, 16, v14
	v_and_b32_e32 v83, 0xffff0000, v14
	v_lshlrev_b32_e32 v84, 16, v15
	v_and_b32_e32 v85, 0xffff0000, v15
	v_lshlrev_b32_e32 v86, 16, v16
	v_and_b32_e32 v87, 0xffff0000, v16
	v_lshlrev_b32_e32 v88, 16, v17
	v_and_b32_e32 v89, 0xffff0000, v17
	v_lshlrev_b32_e32 v90, 16, v18
	v_and_b32_e32 v91, 0xffff0000, v18
	v_lshlrev_b32_e32 v92, 16, v19
	v_and_b32_e32 v93, 0xffff0000, v19
	v_pk_mul_f32 v[28:29], v[78:79], s[56:57]
	v_pk_mul_f32 v[30:31], v[80:81], s[56:57]
	v_pk_mul_f32 v[32:33], v[82:83], s[56:57]
	v_pk_mul_f32 v[34:35], v[84:85], s[56:57]
	v_pk_mul_f32 v[36:37], v[86:87], s[56:57]
	v_pk_mul_f32 v[38:39], v[88:89], s[56:57]
	v_pk_mul_f32 v[40:41], v[90:91], s[56:57]
	v_pk_mul_f32 v[42:43], v[92:93], s[56:57]
	v_exp_f32_e32 v28, v28
	v_exp_f32_e32 v29, v29
	v_exp_f32_e32 v30, v30
	v_exp_f32_e32 v31, v31
	v_exp_f32_e32 v32, v32
	v_exp_f32_e32 v33, v33
	v_exp_f32_e32 v34, v34
	v_exp_f32_e32 v35, v35
	v_exp_f32_e32 v36, v36
	v_exp_f32_e32 v37, v37
	v_exp_f32_e32 v38, v38
	v_exp_f32_e32 v39, v39
	v_exp_f32_e32 v40, v40
	v_exp_f32_e32 v41, v41
	v_exp_f32_e32 v42, v42
	v_exp_f32_e32 v43, v43
	v_pk_add_f32 v[28:29], v[28:29], s[54:55]
	v_pk_add_f32 v[30:31], v[30:31], s[54:55]
	v_pk_add_f32 v[32:33], v[32:33], s[54:55]
	v_pk_add_f32 v[34:35], v[34:35], s[54:55]
	v_pk_add_f32 v[36:37], v[36:37], s[54:55]
	v_pk_add_f32 v[38:39], v[38:39], s[54:55]
	v_pk_add_f32 v[40:41], v[40:41], s[54:55]
	v_pk_add_f32 v[42:43], v[42:43], s[54:55]
	v_rcp_f32_e32 v28, v28
	v_rcp_f32_e32 v29, v29
	v_rcp_f32_e32 v30, v30
	v_rcp_f32_e32 v31, v31
	v_rcp_f32_e32 v32, v32
	v_rcp_f32_e32 v33, v33
	v_rcp_f32_e32 v34, v34
	v_rcp_f32_e32 v35, v35
	v_rcp_f32_e32 v36, v36
	v_rcp_f32_e32 v37, v37
	v_rcp_f32_e32 v38, v38
	v_rcp_f32_e32 v39, v39
	v_rcp_f32_e32 v40, v40
	v_rcp_f32_e32 v41, v41
	v_rcp_f32_e32 v42, v42
	v_rcp_f32_e32 v43, v43
	v_pk_mul_f32 v[28:29], v[78:79], v[28:29]
	v_pk_mul_f32 v[30:31], v[80:81], v[30:31]
	v_pk_mul_f32 v[32:33], v[82:83], v[32:33]
	v_pk_mul_f32 v[34:35], v[84:85], v[34:35]
	v_pk_mul_f32 v[36:37], v[86:87], v[36:37]
	v_pk_mul_f32 v[38:39], v[88:89], v[38:39]
	v_pk_mul_f32 v[40:41], v[90:91], v[40:41]
	v_pk_mul_f32 v[42:43], v[92:93], v[42:43]
	v_pk_mul_f32 v[28:29], v[46:47], v[28:29]
	v_pk_mul_f32 v[30:31], v[48:49], v[30:31]
	v_pk_mul_f32 v[32:33], v[50:51], v[32:33]
	v_pk_mul_f32 v[34:35], v[52:53], v[34:35]
	v_pk_mul_f32 v[36:37], v[54:55], v[36:37]
	v_pk_mul_f32 v[38:39], v[56:57], v[38:39]
	v_pk_mul_f32 v[40:41], v[58:59], v[40:41]
	v_pk_mul_f32 v[42:43], v[60:61], v[42:43]
	v_cvt_pk_bf16_f32 v78, v28, v29
	v_cvt_pk_bf16_f32 v79, v30, v31
	v_cvt_pk_bf16_f32 v80, v32, v33
	v_cvt_pk_bf16_f32 v81, v34, v35
	v_cvt_pk_bf16_f32 v82, v36, v37
	v_cvt_pk_bf16_f32 v83, v38, v39
	v_cvt_pk_bf16_f32 v84, v40, v41
	v_cvt_pk_bf16_f32 v85, v42, v43
	global_store_dwordx2 v[4:5], v[78:79], off offset:384
	global_store_dwordx2 v[4:5], v[80:81], off offset:400
	global_store_dwordx2 v[4:5], v[82:83], off offset:416
	global_store_dwordx2 v[4:5], v[84:85], off offset:432
	v_lshlrev_b32_e32 v78, 16, v20
	v_and_b32_e32 v79, 0xffff0000, v20
	v_lshlrev_b32_e32 v80, 16, v21
	v_and_b32_e32 v81, 0xffff0000, v21
	v_lshlrev_b32_e32 v82, 16, v22
	v_and_b32_e32 v83, 0xffff0000, v22
	v_lshlrev_b32_e32 v84, 16, v23
	v_and_b32_e32 v85, 0xffff0000, v23
	v_lshlrev_b32_e32 v86, 16, v24
	v_and_b32_e32 v87, 0xffff0000, v24
	v_lshlrev_b32_e32 v88, 16, v25
	v_and_b32_e32 v89, 0xffff0000, v25
	v_lshlrev_b32_e32 v90, 16, v26
	v_and_b32_e32 v91, 0xffff0000, v26
	v_lshlrev_b32_e32 v92, 16, v27
	v_and_b32_e32 v93, 0xffff0000, v27
	v_pk_mul_f32 v[28:29], v[78:79], s[56:57]
	v_pk_mul_f32 v[30:31], v[80:81], s[56:57]
	v_pk_mul_f32 v[32:33], v[82:83], s[56:57]
	v_pk_mul_f32 v[34:35], v[84:85], s[56:57]
	v_pk_mul_f32 v[36:37], v[86:87], s[56:57]
	v_pk_mul_f32 v[38:39], v[88:89], s[56:57]
	v_pk_mul_f32 v[40:41], v[90:91], s[56:57]
	v_pk_mul_f32 v[42:43], v[92:93], s[56:57]
	v_exp_f32_e32 v28, v28
	v_exp_f32_e32 v29, v29
	v_exp_f32_e32 v30, v30
	v_exp_f32_e32 v31, v31
	v_exp_f32_e32 v32, v32
	v_exp_f32_e32 v33, v33
	v_exp_f32_e32 v34, v34
	v_exp_f32_e32 v35, v35
	v_exp_f32_e32 v36, v36
	v_exp_f32_e32 v37, v37
	v_exp_f32_e32 v38, v38
	v_exp_f32_e32 v39, v39
	v_exp_f32_e32 v40, v40
	v_exp_f32_e32 v41, v41
	v_exp_f32_e32 v42, v42
	v_exp_f32_e32 v43, v43
	v_pk_add_f32 v[28:29], v[28:29], s[54:55]
	v_pk_add_f32 v[30:31], v[30:31], s[54:55]
	v_pk_add_f32 v[32:33], v[32:33], s[54:55]
	v_pk_add_f32 v[34:35], v[34:35], s[54:55]
	v_pk_add_f32 v[36:37], v[36:37], s[54:55]
	v_pk_add_f32 v[38:39], v[38:39], s[54:55]
	v_pk_add_f32 v[40:41], v[40:41], s[54:55]
	v_pk_add_f32 v[42:43], v[42:43], s[54:55]
	v_rcp_f32_e32 v28, v28
	v_rcp_f32_e32 v29, v29
	v_rcp_f32_e32 v30, v30
	v_rcp_f32_e32 v31, v31
	v_rcp_f32_e32 v32, v32
	v_rcp_f32_e32 v33, v33
	v_rcp_f32_e32 v34, v34
	v_rcp_f32_e32 v35, v35
	v_rcp_f32_e32 v36, v36
	v_rcp_f32_e32 v37, v37
	v_rcp_f32_e32 v38, v38
	v_rcp_f32_e32 v39, v39
	v_rcp_f32_e32 v40, v40
	v_rcp_f32_e32 v41, v41
	v_rcp_f32_e32 v42, v42
	v_rcp_f32_e32 v43, v43
	v_pk_mul_f32 v[28:29], v[78:79], v[28:29]
	v_pk_mul_f32 v[30:31], v[80:81], v[30:31]
	v_pk_mul_f32 v[32:33], v[82:83], v[32:33]
	v_pk_mul_f32 v[34:35], v[84:85], v[34:35]
	v_pk_mul_f32 v[36:37], v[86:87], v[36:37]
	v_pk_mul_f32 v[38:39], v[88:89], v[38:39]
	v_pk_mul_f32 v[40:41], v[90:91], v[40:41]
	v_pk_mul_f32 v[42:43], v[92:93], v[42:43]
	v_pk_mul_f32 v[28:29], v[62:63], v[28:29]
	v_pk_mul_f32 v[30:31], v[64:65], v[30:31]
	v_pk_mul_f32 v[32:33], v[66:67], v[32:33]
	v_pk_mul_f32 v[34:35], v[68:69], v[34:35]
	v_pk_mul_f32 v[36:37], v[70:71], v[36:37]
	v_pk_mul_f32 v[38:39], v[72:73], v[38:39]
	v_pk_mul_f32 v[40:41], v[74:75], v[40:41]
	v_pk_mul_f32 v[42:43], v[76:77], v[42:43]
	v_cvt_pk_bf16_f32 v78, v28, v29
	v_cvt_pk_bf16_f32 v79, v30, v31
	v_cvt_pk_bf16_f32 v80, v32, v33
	v_cvt_pk_bf16_f32 v81, v34, v35
	v_cvt_pk_bf16_f32 v82, v36, v37
	v_cvt_pk_bf16_f32 v83, v38, v39
	v_cvt_pk_bf16_f32 v84, v40, v41
	v_cvt_pk_bf16_f32 v85, v42, v43
	global_store_dwordx2 v[4:5], v[78:79], off offset:448
	global_store_dwordx2 v[4:5], v[80:81], off offset:464
	global_store_dwordx2 v[4:5], v[82:83], off offset:480
	global_store_dwordx2 v[4:5], v[84:85], off offset:496
	s_waitcnt vmcnt(0)
	s_mov_b32 m0, s59
	v_readlane_b32 s38, v250, 39
	v_readlane_b32 s39, v250, 40
	s_barrier
